# phase C conv chunks: per-row (sum,sumsq) wave reductions via DPP/permlane-swap instead of 6 serialized ds_bpermute rounds (bitwise-identical sums)
# speedup vs baseline: 1.0046x; 1.0046x over previous
.LBB0_453:
	s_mul_i32 s12, s3, 44
	s_add_i32 s11, s11, s3
	s_add_i32 s10, s10, s7
	s_add_i32 s9, s9, s3
	s_add_i32 s8, s8, s12
	s_cmpk_gt_i32 s11, 0xfa
	s_waitcnt vmcnt(63) expcnt(7) lgkmcnt(0)
	s_cbranch_scc1 .LBB0_543

.LBB0_469:
	v_add_u32_e32 v86, 0xffff0000, v177
	v_add_u32_e32 v87, 0xffff0800, v177
	v_add_u32_e32 v88, 0xffff1000, v177
	v_add_u32_e32 v89, 0xffff1800, v177
	v_add_u32_e32 v90, 0xffff2000, v177
	v_add_u32_e32 v91, 0xffff2800, v177
	v_add_u32_e32 v92, 0xffff3000, v177
	v_add_u32_e32 v93, 0xffff3800, v177
	ds_read_b32 v94, v86
	ds_read_b32 v95, v87
	ds_read_b32 v88, v88
	ds_read_b32 v89, v89
	ds_read_b32 v96, v90
	ds_read_b32 v97, v91
	ds_read_b32 v98, v92
	ds_read_b32 v99, v93
	s_waitcnt lgkmcnt(0)
	v_lshlrev_b32_e32 v86, 16, v94
	v_and_b32_e32 v87, 0xffff0000, v94
	v_pk_fma_f32 v[86:87], v[4:5], v[86:87], v[74:75]
	s_waitcnt lgkmcnt(0)
	v_lshlrev_b32_e32 v132, 16, v95
	v_and_b32_e32 v133, 0xffff0000, v95
	v_pk_fma_f32 v[86:87], v[6:7], v[132:133], v[86:87]
	s_waitcnt lgkmcnt(0)
	v_lshlrev_b32_e32 v90, 16, v88
	v_and_b32_e32 v91, 0xffff0000, v88
	v_pk_fma_f32 v[86:87], v[8:9], v[90:91], v[86:87]
	s_waitcnt lgkmcnt(0)
	v_lshlrev_b32_e32 v92, 16, v89
	v_and_b32_e32 v93, 0xffff0000, v89
	v_pk_fma_f32 v[86:87], v[10:11], v[92:93], v[86:87]
	s_waitcnt lgkmcnt(0)
	v_lshlrev_b32_e32 v94, 16, v96
	v_and_b32_e32 v95, 0xffff0000, v96
	v_pk_fma_f32 v[86:87], v[12:13], v[94:95], v[86:87]
	s_waitcnt lgkmcnt(0)
	v_lshlrev_b32_e32 v114, 16, v97
	v_and_b32_e32 v115, 0xffff0000, v97
	v_pk_fma_f32 v[88:89], v[14:15], v[114:115], v[86:87]
	s_waitcnt lgkmcnt(0)
	v_lshlrev_b32_e32 v86, 16, v98
	v_and_b32_e32 v87, 0xffff0000, v98
	v_pk_fma_f32 v[96:97], v[16:17], v[86:87], v[88:89]
	s_waitcnt lgkmcnt(0)
	v_lshlrev_b32_e32 v88, 16, v99
	v_and_b32_e32 v89, 0xffff0000, v99
	v_pk_fma_f32 v[98:99], v[18:19], v[88:89], v[96:97]
	v_add_u32_e32 v96, 0xffff4000, v177
	v_add_u32_e32 v97, 0xffff4800, v177
	v_add_u32_e32 v100, 0xffff5000, v177
	v_add_u32_e32 v101, 0xffff5800, v177
	v_add_u32_e32 v102, 0xffff6000, v177
	v_add_u32_e32 v103, 0xffff6800, v177
	v_add_u32_e32 v104, 0xffff7000, v177
	v_add_u32_e32 v105, 0xffff7800, v177
	ds_read_b32 v106, v96
	ds_read_b32 v107, v97
	ds_read_b32 v108, v100
	ds_read_b32 v109, v101
	ds_read_b32 v110, v102
	ds_read_b32 v111, v103
	ds_read_b32 v112, v104
	ds_read_b32 v116, v105
	s_waitcnt lgkmcnt(0)
	v_lshlrev_b32_e32 v96, 16, v106
	v_and_b32_e32 v97, 0xffff0000, v106
	v_pk_fma_f32 v[100:101], v[28:29], v[96:97], v[98:99]
	s_waitcnt lgkmcnt(0)
	v_lshlrev_b32_e32 v98, 16, v107
	v_and_b32_e32 v99, 0xffff0000, v107
	v_pk_fma_f32 v[102:103], v[30:31], v[98:99], v[100:101]
	s_waitcnt lgkmcnt(0)
	v_lshlrev_b32_e32 v100, 16, v108
	v_and_b32_e32 v101, 0xffff0000, v108
	v_pk_fma_f32 v[104:105], v[32:33], v[100:101], v[102:103]
	s_waitcnt lgkmcnt(0)
	v_lshlrev_b32_e32 v102, 16, v109
	v_and_b32_e32 v103, 0xffff0000, v109
	v_pk_fma_f32 v[106:107], v[34:35], v[102:103], v[104:105]
	s_waitcnt lgkmcnt(0)
	v_lshlrev_b32_e32 v104, 16, v110
	v_and_b32_e32 v105, 0xffff0000, v110
	v_pk_fma_f32 v[108:109], v[36:37], v[104:105], v[106:107]
	s_waitcnt lgkmcnt(0)
	v_lshlrev_b32_e32 v106, 16, v111
	v_and_b32_e32 v107, 0xffff0000, v111
	v_pk_fma_f32 v[110:111], v[38:39], v[106:107], v[108:109]
	s_waitcnt lgkmcnt(0)
	v_lshlrev_b32_e32 v108, 16, v112
	v_and_b32_e32 v109, 0xffff0000, v112
	v_pk_fma_f32 v[112:113], v[40:41], v[108:109], v[110:111]
	s_waitcnt lgkmcnt(0)
	v_lshlrev_b32_e32 v110, 16, v116
	v_and_b32_e32 v111, 0xffff0000, v116
	v_add_u32_e32 v116, 0xffff8000, v177
	v_add_u32_e32 v117, 0xffff8800, v177
	v_pk_fma_f32 v[112:113], v[42:43], v[110:111], v[112:113]
	v_add_u32_e32 v118, 0xffff9000, v177
	v_add_u32_e32 v119, 0xffff9800, v177
	v_add_u32_e32 v120, 0xffffa000, v177
	v_add_u32_e32 v121, 0xffffa800, v177
	v_add_u32_e32 v122, 0xffffb000, v177
	v_add_u32_e32 v123, 0xffffb800, v177
	ds_read_b32 v124, v116
	ds_read_b32 v125, v117
	ds_read_b32 v126, v118
	ds_read_b32 v127, v119
	ds_read_b32 v128, v120
	ds_read_b32 v129, v121
	ds_read_b32 v130, v122
	ds_read_b32 v131, v123
	s_waitcnt lgkmcnt(0)
	v_lshlrev_b32_e32 v116, 16, v124
	v_and_b32_e32 v117, 0xffff0000, v124
	v_pk_fma_f32 v[112:113], v[44:45], v[116:117], v[112:113]
	s_waitcnt lgkmcnt(0)
	v_lshlrev_b32_e32 v118, 16, v125
	v_and_b32_e32 v119, 0xffff0000, v125
	v_pk_fma_f32 v[112:113], v[46:47], v[118:119], v[112:113]
	s_waitcnt lgkmcnt(0)
	v_lshlrev_b32_e32 v120, 16, v126
	v_and_b32_e32 v121, 0xffff0000, v126
	v_pk_fma_f32 v[112:113], v[48:49], v[120:121], v[112:113]
	s_waitcnt lgkmcnt(0)
	v_lshlrev_b32_e32 v122, 16, v127
	v_and_b32_e32 v123, 0xffff0000, v127
	v_pk_fma_f32 v[112:113], v[50:51], v[122:123], v[112:113]
	s_waitcnt lgkmcnt(0)
	v_lshlrev_b32_e32 v124, 16, v128
	v_and_b32_e32 v125, 0xffff0000, v128
	v_pk_fma_f32 v[112:113], v[52:53], v[124:125], v[112:113]
	s_waitcnt lgkmcnt(0)
	v_lshlrev_b32_e32 v126, 16, v129
	v_and_b32_e32 v127, 0xffff0000, v129
	v_pk_fma_f32 v[112:113], v[54:55], v[126:127], v[112:113]
	s_waitcnt lgkmcnt(0)
	v_lshlrev_b32_e32 v128, 16, v130
	v_and_b32_e32 v129, 0xffff0000, v130
	v_pk_fma_f32 v[112:113], v[56:57], v[128:129], v[112:113]
	s_waitcnt lgkmcnt(0)
	v_lshlrev_b32_e32 v130, 16, v131
	v_and_b32_e32 v131, 0xffff0000, v131
	v_add_u32_e32 v134, 0xffffc000, v177
	v_add_u32_e32 v135, 0xffffc800, v177
	v_pk_fma_f32 v[112:113], v[58:59], v[130:131], v[112:113]
	v_add_u32_e32 v136, 0xffffd000, v177
	v_add_u32_e32 v137, 0xffffd800, v177
	v_add_u32_e32 v138, 0xffffe000, v177
	v_add_u32_e32 v139, 0xffffe800, v177
	v_add_u32_e32 v140, 0xfffff000, v177
	v_add_u32_e32 v141, 0xfffff800, v177
	ds_read_b32 v142, v134
	ds_read_b32 v143, v135
	ds_read_b32 v144, v136
	ds_read_b32 v145, v137
	ds_read_b32 v146, v138
	ds_read_b32 v147, v139
	ds_read_b32 v148, v140
	ds_read_b32 v158, v141
	s_waitcnt lgkmcnt(0)
	v_lshlrev_b32_e32 v134, 16, v142
	v_and_b32_e32 v135, 0xffff0000, v142
	v_pk_fma_f32 v[112:113], v[60:61], v[134:135], v[112:113]
	s_waitcnt lgkmcnt(0)
	v_lshlrev_b32_e32 v136, 16, v143
	v_and_b32_e32 v137, 0xffff0000, v143
	v_pk_fma_f32 v[112:113], v[62:63], v[136:137], v[112:113]
	s_waitcnt lgkmcnt(0)
	v_lshlrev_b32_e32 v138, 16, v144
	v_and_b32_e32 v139, 0xffff0000, v144
	v_pk_fma_f32 v[112:113], v[64:65], v[138:139], v[112:113]
	s_waitcnt lgkmcnt(0)
	v_lshlrev_b32_e32 v140, 16, v145
	v_and_b32_e32 v141, 0xffff0000, v145
	v_pk_fma_f32 v[112:113], v[66:67], v[140:141], v[112:113]
	s_waitcnt lgkmcnt(0)
	v_lshlrev_b32_e32 v142, 16, v146
	v_and_b32_e32 v143, 0xffff0000, v146
	v_pk_fma_f32 v[112:113], v[68:69], v[142:143], v[112:113]
	s_waitcnt lgkmcnt(0)
	v_lshlrev_b32_e32 v144, 16, v147
	v_and_b32_e32 v145, 0xffff0000, v147
	v_pk_fma_f32 v[112:113], v[70:71], v[144:145], v[112:113]
	s_waitcnt lgkmcnt(0)
	v_lshlrev_b32_e32 v146, 16, v148
	v_and_b32_e32 v147, 0xffff0000, v148
	v_pk_fma_f32 v[112:113], v[72:73], v[146:147], v[112:113]
	s_nop 0
	v_pk_mul_f32 v[148:149], v[112:113], v[112:113]
	v_mov_b32_e32 v150, v112
	v_mov_b32_e32 v151, v148
	v_mov_b32_e32 v148, v113
	v_pk_add_f32 v[148:149], v[150:151], v[148:149]
	s_nop 1
	v_add_f32_dpp v148, v148, v148 quad_perm:[1,0,3,2] row_mask:0xf bank_mask:0xf
	v_add_f32_dpp v149, v149, v149 quad_perm:[1,0,3,2] row_mask:0xf bank_mask:0xf
	s_waitcnt lgkmcnt(0)
	s_nop 0
	s_nop 1
	v_add_f32_dpp v148, v148, v148 quad_perm:[2,3,0,1] row_mask:0xf bank_mask:0xf
	v_add_f32_dpp v149, v149, v149 quad_perm:[2,3,0,1] row_mask:0xf bank_mask:0xf
	s_waitcnt lgkmcnt(0)
	s_nop 0
	s_nop 1
	v_add_f32_dpp v148, v148, v148 row_half_mirror row_mask:0xf bank_mask:0xf
	v_add_f32_dpp v149, v149, v149 row_half_mirror row_mask:0xf bank_mask:0xf
	s_waitcnt lgkmcnt(0)
	s_nop 0
	s_nop 1
	v_add_f32_dpp v150, v148, v148 row_mirror row_mask:0xf bank_mask:0xf
	v_add_f32_dpp v151, v149, v149 row_mirror row_mask:0xf bank_mask:0xf
	s_waitcnt lgkmcnt(0)
	s_nop 0
	v_mov_b32_e32 v152, v150
	v_mov_b32_e32 v153, v151
	s_nop 1
	v_permlane16_swap_b32_e32 v152, v150
	v_permlane16_swap_b32_e32 v153, v151
	s_nop 1
	ds_read2st64_b32 v[156:157], v177 offset1:8
	ds_read2st64_b32 v[154:155], v177 offset0:16 offset1:24
	ds_read2st64_b32 v[148:149], v177 offset0:32 offset1:40
	s_waitcnt lgkmcnt(0)
	v_pk_add_f32 v[150:151], v[150:151], v[152:153]
	v_mov_b32_e32 v152, v150
	v_mov_b32_e32 v153, v151
	s_nop 1
	v_permlane32_swap_b32_e32 v152, v150
	v_permlane32_swap_b32_e32 v153, v151
	s_nop 1
	s_and_saveexec_b64 s[16:17], s[42:43]
	s_cbranch_execz .LBB0_471
	s_add_i32 s18, s15, 0
	s_add_i32 s18, s18, 0x1f000
	s_waitcnt lgkmcnt(0)
	v_pk_add_f32 v[150:151], v[150:151], v[152:153]
	v_mov_b32_e32 v152, s18
	ds_write_b64 v152, v[150:151]
.LBB0_471:
	s_or_b64 exec, exec, s[16:17]
	v_pk_fma_f32 v[132:133], v[4:5], v[132:133], v[74:75]
	v_lshlrev_b32_e32 v150, 16, v158
	v_pk_fma_f32 v[132:133], v[6:7], v[90:91], v[132:133]
	v_and_b32_e32 v151, 0xffff0000, v158
	v_pk_fma_f32 v[132:133], v[8:9], v[92:93], v[132:133]
	s_nop 0
	v_pk_fma_f32 v[132:133], v[10:11], v[94:95], v[132:133]
	s_nop 0
	v_pk_fma_f32 v[132:133], v[12:13], v[114:115], v[132:133]
	s_nop 0
	v_pk_fma_f32 v[132:133], v[14:15], v[86:87], v[132:133]
	s_nop 0
	v_pk_fma_f32 v[132:133], v[16:17], v[88:89], v[132:133]
	s_nop 0
	v_pk_fma_f32 v[132:133], v[18:19], v[96:97], v[132:133]
	s_nop 0
	v_pk_fma_f32 v[132:133], v[28:29], v[98:99], v[132:133]
	s_nop 0
	v_pk_fma_f32 v[132:133], v[30:31], v[100:101], v[132:133]
	s_nop 0
	v_pk_fma_f32 v[132:133], v[32:33], v[102:103], v[132:133]
	s_nop 0
	v_pk_fma_f32 v[132:133], v[34:35], v[104:105], v[132:133]
	s_nop 0
	v_pk_fma_f32 v[132:133], v[36:37], v[106:107], v[132:133]
	s_nop 0
	v_pk_fma_f32 v[132:133], v[38:39], v[108:109], v[132:133]
	s_nop 0
	v_pk_fma_f32 v[132:133], v[40:41], v[110:111], v[132:133]
	s_nop 0
	v_pk_fma_f32 v[132:133], v[42:43], v[116:117], v[132:133]
	s_nop 0
	v_pk_fma_f32 v[132:133], v[44:45], v[118:119], v[132:133]
	s_nop 0
	v_pk_fma_f32 v[132:133], v[46:47], v[120:121], v[132:133]
	s_nop 0
	v_pk_fma_f32 v[132:133], v[48:49], v[122:123], v[132:133]
	s_nop 0
	v_pk_fma_f32 v[132:133], v[50:51], v[124:125], v[132:133]
	s_nop 0
	v_pk_fma_f32 v[132:133], v[52:53], v[126:127], v[132:133]
	s_nop 0
	v_pk_fma_f32 v[132:133], v[54:55], v[128:129], v[132:133]
	s_nop 0
	v_pk_fma_f32 v[132:133], v[56:57], v[130:131], v[132:133]
	s_nop 0
	v_pk_fma_f32 v[132:133], v[58:59], v[134:135], v[132:133]
	s_nop 0
	v_pk_fma_f32 v[132:133], v[60:61], v[136:137], v[132:133]
	s_nop 0
	v_pk_fma_f32 v[132:133], v[62:63], v[138:139], v[132:133]
	s_nop 0
	v_pk_fma_f32 v[132:133], v[64:65], v[140:141], v[132:133]
	s_nop 0
	v_pk_fma_f32 v[132:133], v[66:67], v[142:143], v[132:133]
	s_nop 0
	v_pk_fma_f32 v[132:133], v[68:69], v[144:145], v[132:133]
	s_nop 0
	v_pk_fma_f32 v[132:133], v[70:71], v[146:147], v[132:133]
	s_nop 0
	v_pk_fma_f32 v[132:133], v[72:73], v[150:151], v[132:133]
	s_waitcnt lgkmcnt(0)
	v_pk_mul_f32 v[152:153], v[132:133], v[132:133]
	v_mov_b32_e32 v158, v132
	v_mov_b32_e32 v159, v152
	v_mov_b32_e32 v152, v133
	v_pk_add_f32 v[152:153], v[158:159], v[152:153]
	s_nop 1
	v_add_f32_dpp v152, v152, v152 quad_perm:[1,0,3,2] row_mask:0xf bank_mask:0xf
	v_add_f32_dpp v153, v153, v153 quad_perm:[1,0,3,2] row_mask:0xf bank_mask:0xf
	s_waitcnt lgkmcnt(0)
	s_nop 0
	s_nop 1
	v_add_f32_dpp v152, v152, v152 quad_perm:[2,3,0,1] row_mask:0xf bank_mask:0xf
	v_add_f32_dpp v153, v153, v153 quad_perm:[2,3,0,1] row_mask:0xf bank_mask:0xf
	s_waitcnt lgkmcnt(0)
	s_nop 0
	s_nop 1
	v_add_f32_dpp v152, v152, v152 row_half_mirror row_mask:0xf bank_mask:0xf
	v_add_f32_dpp v153, v153, v153 row_half_mirror row_mask:0xf bank_mask:0xf
	s_waitcnt lgkmcnt(0)
	s_nop 0
	s_nop 1
	v_add_f32_dpp v152, v152, v152 row_mirror row_mask:0xf bank_mask:0xf
	v_add_f32_dpp v153, v153, v153 row_mirror row_mask:0xf bank_mask:0xf
	s_waitcnt lgkmcnt(0)
	s_nop 0
	v_mov_b32_e32 v158, v152
	v_mov_b32_e32 v159, v153
	s_nop 1
	v_permlane16_swap_b32_e32 v158, v152
	v_permlane16_swap_b32_e32 v159, v153
	s_nop 1
	s_waitcnt lgkmcnt(0)
	v_pk_add_f32 v[152:153], v[152:153], v[158:159]
	v_mov_b32_e32 v158, v152
	v_mov_b32_e32 v159, v153
	s_nop 1
	v_permlane32_swap_b32_e32 v158, v152
	v_permlane32_swap_b32_e32 v159, v153
	s_nop 1
	s_and_saveexec_b64 s[16:17], s[42:43]
	s_cbranch_execz .LBB0_473
	s_add_i32 s18, s15, 0
	s_add_i32 s18, s18, 0x1f008
	s_waitcnt lgkmcnt(0)
	v_pk_add_f32 v[152:153], v[152:153], v[158:159]
	v_mov_b32_e32 v158, s18
	ds_write_b64 v158, v[152:153]
.LBB0_473:
	s_or_b64 exec, exec, s[16:17]
	v_pk_fma_f32 v[90:91], v[4:5], v[90:91], v[74:75]
	v_lshlrev_b32_e32 v152, 16, v156
	v_pk_fma_f32 v[90:91], v[6:7], v[92:93], v[90:91]
	v_and_b32_e32 v153, 0xffff0000, v156
	v_pk_fma_f32 v[90:91], v[8:9], v[94:95], v[90:91]
	s_nop 0
	v_pk_fma_f32 v[90:91], v[10:11], v[114:115], v[90:91]
	s_nop 0
	v_pk_fma_f32 v[90:91], v[12:13], v[86:87], v[90:91]
	s_nop 0
	v_pk_fma_f32 v[90:91], v[14:15], v[88:89], v[90:91]
	s_nop 0
	v_pk_fma_f32 v[90:91], v[16:17], v[96:97], v[90:91]
	s_nop 0
	v_pk_fma_f32 v[90:91], v[18:19], v[98:99], v[90:91]
	s_nop 0
	v_pk_fma_f32 v[90:91], v[28:29], v[100:101], v[90:91]
	s_nop 0
	v_pk_fma_f32 v[90:91], v[30:31], v[102:103], v[90:91]
	s_nop 0
	v_pk_fma_f32 v[90:91], v[32:33], v[104:105], v[90:91]
	s_nop 0
	v_pk_fma_f32 v[90:91], v[34:35], v[106:107], v[90:91]
	s_nop 0
	v_pk_fma_f32 v[90:91], v[36:37], v[108:109], v[90:91]
	s_nop 0
	v_pk_fma_f32 v[90:91], v[38:39], v[110:111], v[90:91]
	s_nop 0
	v_pk_fma_f32 v[90:91], v[40:41], v[116:117], v[90:91]
	s_nop 0
	v_pk_fma_f32 v[90:91], v[42:43], v[118:119], v[90:91]
	s_nop 0
	v_pk_fma_f32 v[90:91], v[44:45], v[120:121], v[90:91]
	s_nop 0
	v_pk_fma_f32 v[90:91], v[46:47], v[122:123], v[90:91]
	s_nop 0
	v_pk_fma_f32 v[90:91], v[48:49], v[124:125], v[90:91]
	s_nop 0
	v_pk_fma_f32 v[90:91], v[50:51], v[126:127], v[90:91]
	s_nop 0
	v_pk_fma_f32 v[90:91], v[52:53], v[128:129], v[90:91]
	s_nop 0
	v_pk_fma_f32 v[90:91], v[54:55], v[130:131], v[90:91]
	s_nop 0
	v_pk_fma_f32 v[90:91], v[56:57], v[134:135], v[90:91]
	s_nop 0
	v_pk_fma_f32 v[90:91], v[58:59], v[136:137], v[90:91]
	s_nop 0
	v_pk_fma_f32 v[90:91], v[60:61], v[138:139], v[90:91]
	s_nop 0
	v_pk_fma_f32 v[90:91], v[62:63], v[140:141], v[90:91]
	s_nop 0
	v_pk_fma_f32 v[90:91], v[64:65], v[142:143], v[90:91]
	s_nop 0
	v_pk_fma_f32 v[90:91], v[66:67], v[144:145], v[90:91]
	s_nop 0
	v_pk_fma_f32 v[90:91], v[68:69], v[146:147], v[90:91]
	s_nop 0
	v_pk_fma_f32 v[90:91], v[70:71], v[150:151], v[90:91]
	s_nop 0
	v_pk_fma_f32 v[90:91], v[72:73], v[152:153], v[90:91]
	s_waitcnt lgkmcnt(0)
	v_pk_mul_f32 v[158:159], v[90:91], v[90:91]
	v_mov_b32_e32 v160, v90
	v_mov_b32_e32 v161, v158
	v_mov_b32_e32 v158, v91
	v_pk_add_f32 v[158:159], v[160:161], v[158:159]
	s_nop 1
	v_add_f32_dpp v158, v158, v158 quad_perm:[1,0,3,2] row_mask:0xf bank_mask:0xf
	v_add_f32_dpp v159, v159, v159 quad_perm:[1,0,3,2] row_mask:0xf bank_mask:0xf
	s_waitcnt lgkmcnt(0)
	s_nop 0
	s_nop 1
	v_add_f32_dpp v158, v158, v158 quad_perm:[2,3,0,1] row_mask:0xf bank_mask:0xf
	v_add_f32_dpp v159, v159, v159 quad_perm:[2,3,0,1] row_mask:0xf bank_mask:0xf
	s_waitcnt lgkmcnt(0)
	s_nop 0
	s_nop 1
	v_add_f32_dpp v158, v158, v158 row_half_mirror row_mask:0xf bank_mask:0xf
	v_add_f32_dpp v159, v159, v159 row_half_mirror row_mask:0xf bank_mask:0xf
	s_waitcnt lgkmcnt(0)
	s_nop 0
	s_nop 1
	v_add_f32_dpp v158, v158, v158 row_mirror row_mask:0xf bank_mask:0xf
	v_add_f32_dpp v159, v159, v159 row_mirror row_mask:0xf bank_mask:0xf
	s_waitcnt lgkmcnt(0)
	s_nop 0
	v_mov_b32_e32 v160, v158
	v_mov_b32_e32 v161, v159
	s_nop 1
	v_permlane16_swap_b32_e32 v160, v158
	v_permlane16_swap_b32_e32 v161, v159
	s_nop 1
	s_waitcnt lgkmcnt(0)
	v_pk_add_f32 v[158:159], v[158:159], v[160:161]
	v_mov_b32_e32 v160, v158
	v_mov_b32_e32 v161, v159
	s_nop 1
	v_permlane32_swap_b32_e32 v160, v158
	v_permlane32_swap_b32_e32 v161, v159
	s_nop 1
	s_and_saveexec_b64 s[16:17], s[42:43]
	s_cbranch_execz .LBB0_475
	s_add_i32 s18, s15, 0
	s_add_i32 s18, s18, 0x1f010
	s_waitcnt lgkmcnt(0)
	v_pk_add_f32 v[158:159], v[158:159], v[160:161]
	v_mov_b32_e32 v156, s18
	ds_write_b64 v156, v[158:159]
.LBB0_475:
	s_or_b64 exec, exec, s[16:17]
	v_pk_fma_f32 v[92:93], v[4:5], v[92:93], v[74:75]
	v_lshlrev_b32_e32 v156, 16, v157
	v_pk_fma_f32 v[92:93], v[6:7], v[94:95], v[92:93]
	v_and_b32_e32 v157, 0xffff0000, v157
	v_pk_fma_f32 v[92:93], v[8:9], v[114:115], v[92:93]
	s_nop 0
	v_pk_fma_f32 v[92:93], v[10:11], v[86:87], v[92:93]
	s_nop 0
	v_pk_fma_f32 v[92:93], v[12:13], v[88:89], v[92:93]
	s_nop 0
	v_pk_fma_f32 v[92:93], v[14:15], v[96:97], v[92:93]
	s_nop 0
	v_pk_fma_f32 v[92:93], v[16:17], v[98:99], v[92:93]
	s_nop 0
	v_pk_fma_f32 v[92:93], v[18:19], v[100:101], v[92:93]
	s_nop 0
	v_pk_fma_f32 v[92:93], v[28:29], v[102:103], v[92:93]
	s_nop 0
	v_pk_fma_f32 v[92:93], v[30:31], v[104:105], v[92:93]
	s_nop 0
	v_pk_fma_f32 v[92:93], v[32:33], v[106:107], v[92:93]
	s_nop 0
	v_pk_fma_f32 v[92:93], v[34:35], v[108:109], v[92:93]
	s_nop 0
	v_pk_fma_f32 v[92:93], v[36:37], v[110:111], v[92:93]
	s_nop 0
	v_pk_fma_f32 v[92:93], v[38:39], v[116:117], v[92:93]
	s_nop 0
	v_pk_fma_f32 v[92:93], v[40:41], v[118:119], v[92:93]
	s_nop 0
	v_pk_fma_f32 v[92:93], v[42:43], v[120:121], v[92:93]
	s_nop 0
	v_pk_fma_f32 v[92:93], v[44:45], v[122:123], v[92:93]
	s_nop 0
	v_pk_fma_f32 v[92:93], v[46:47], v[124:125], v[92:93]
	s_nop 0
	v_pk_fma_f32 v[92:93], v[48:49], v[126:127], v[92:93]
	s_nop 0
	v_pk_fma_f32 v[92:93], v[50:51], v[128:129], v[92:93]
	s_nop 0
	v_pk_fma_f32 v[92:93], v[52:53], v[130:131], v[92:93]
	s_nop 0
	v_pk_fma_f32 v[92:93], v[54:55], v[134:135], v[92:93]
	s_nop 0
	v_pk_fma_f32 v[92:93], v[56:57], v[136:137], v[92:93]
	s_nop 0
	v_pk_fma_f32 v[92:93], v[58:59], v[138:139], v[92:93]
	s_nop 0
	v_pk_fma_f32 v[92:93], v[60:61], v[140:141], v[92:93]
	s_nop 0
	v_pk_fma_f32 v[92:93], v[62:63], v[142:143], v[92:93]
	s_nop 0
	v_pk_fma_f32 v[92:93], v[64:65], v[144:145], v[92:93]
	s_nop 0
	v_pk_fma_f32 v[92:93], v[66:67], v[146:147], v[92:93]
	s_nop 0
	v_pk_fma_f32 v[92:93], v[68:69], v[150:151], v[92:93]
	s_nop 0
	v_pk_fma_f32 v[92:93], v[70:71], v[152:153], v[92:93]
	s_nop 0
	v_pk_fma_f32 v[92:93], v[72:73], v[156:157], v[92:93]
	s_nop 0
	v_pk_mul_f32 v[158:159], v[92:93], v[92:93]
	s_waitcnt lgkmcnt(0)
	v_mov_b32_e32 v160, v92
	s_waitcnt lgkmcnt(0)
	v_mov_b32_e32 v161, v158
	v_mov_b32_e32 v158, v93
	v_pk_add_f32 v[158:159], v[160:161], v[158:159]
	s_nop 1
	v_add_f32_dpp v158, v158, v158 quad_perm:[1,0,3,2] row_mask:0xf bank_mask:0xf
	v_add_f32_dpp v159, v159, v159 quad_perm:[1,0,3,2] row_mask:0xf bank_mask:0xf
	s_waitcnt lgkmcnt(0)
	s_nop 0
	s_nop 1
	v_add_f32_dpp v158, v158, v158 quad_perm:[2,3,0,1] row_mask:0xf bank_mask:0xf
	v_add_f32_dpp v159, v159, v159 quad_perm:[2,3,0,1] row_mask:0xf bank_mask:0xf
	s_waitcnt lgkmcnt(0)
	s_nop 0
	s_nop 1
	v_add_f32_dpp v158, v158, v158 row_half_mirror row_mask:0xf bank_mask:0xf
	v_add_f32_dpp v159, v159, v159 row_half_mirror row_mask:0xf bank_mask:0xf
	s_waitcnt lgkmcnt(0)
	s_nop 0
	s_nop 1
	v_add_f32_dpp v158, v158, v158 row_mirror row_mask:0xf bank_mask:0xf
	v_add_f32_dpp v159, v159, v159 row_mirror row_mask:0xf bank_mask:0xf
	s_waitcnt lgkmcnt(0)
	s_nop 0
	v_mov_b32_e32 v160, v158
	v_mov_b32_e32 v161, v159
	s_nop 1
	v_permlane16_swap_b32_e32 v160, v158
	v_permlane16_swap_b32_e32 v161, v159
	s_nop 1
	s_waitcnt lgkmcnt(0)
	v_pk_add_f32 v[158:159], v[158:159], v[160:161]
	v_mov_b32_e32 v160, v158
	v_mov_b32_e32 v161, v159
	s_nop 1
	v_permlane32_swap_b32_e32 v160, v158
	v_permlane32_swap_b32_e32 v161, v159
	s_nop 1
	s_and_saveexec_b64 s[16:17], s[42:43]
	s_cbranch_execz .LBB0_477
	s_add_i32 s18, s15, 0
	s_add_i32 s18, s18, 0x1f018
	s_waitcnt lgkmcnt(0)
	v_pk_add_f32 v[158:159], v[158:159], v[160:161]
	v_mov_b32_e32 v160, s18
	ds_write_b64 v160, v[158:159]
.LBB0_477:
	s_or_b64 exec, exec, s[16:17]
	v_pk_fma_f32 v[94:95], v[4:5], v[94:95], v[74:75]
	v_lshlrev_b32_e32 v158, 16, v154
	v_pk_fma_f32 v[94:95], v[6:7], v[114:115], v[94:95]
	v_and_b32_e32 v159, 0xffff0000, v154
	v_pk_fma_f32 v[94:95], v[8:9], v[86:87], v[94:95]
	s_nop 0
	v_pk_fma_f32 v[94:95], v[10:11], v[88:89], v[94:95]
	s_nop 0
	v_pk_fma_f32 v[94:95], v[12:13], v[96:97], v[94:95]
	s_nop 0
	v_pk_fma_f32 v[94:95], v[14:15], v[98:99], v[94:95]
	s_nop 0
	v_pk_fma_f32 v[94:95], v[16:17], v[100:101], v[94:95]
	s_nop 0
	v_pk_fma_f32 v[94:95], v[18:19], v[102:103], v[94:95]
	s_nop 0
	v_pk_fma_f32 v[94:95], v[28:29], v[104:105], v[94:95]
	s_nop 0
	v_pk_fma_f32 v[94:95], v[30:31], v[106:107], v[94:95]
	s_nop 0
	v_pk_fma_f32 v[94:95], v[32:33], v[108:109], v[94:95]
	s_nop 0
	v_pk_fma_f32 v[94:95], v[34:35], v[110:111], v[94:95]
	s_nop 0
	v_pk_fma_f32 v[94:95], v[36:37], v[116:117], v[94:95]
	s_nop 0
	v_pk_fma_f32 v[94:95], v[38:39], v[118:119], v[94:95]
	s_nop 0
	v_pk_fma_f32 v[94:95], v[40:41], v[120:121], v[94:95]
	s_nop 0
	v_pk_fma_f32 v[94:95], v[42:43], v[122:123], v[94:95]
	s_nop 0
	v_pk_fma_f32 v[94:95], v[44:45], v[124:125], v[94:95]
	s_nop 0
	v_pk_fma_f32 v[94:95], v[46:47], v[126:127], v[94:95]
	s_nop 0
	v_pk_fma_f32 v[94:95], v[48:49], v[128:129], v[94:95]
	s_nop 0
	v_pk_fma_f32 v[94:95], v[50:51], v[130:131], v[94:95]
	s_nop 0
	v_pk_fma_f32 v[94:95], v[52:53], v[134:135], v[94:95]
	s_nop 0
	v_pk_fma_f32 v[94:95], v[54:55], v[136:137], v[94:95]
	s_nop 0
	v_pk_fma_f32 v[94:95], v[56:57], v[138:139], v[94:95]
	s_nop 0
	v_pk_fma_f32 v[94:95], v[58:59], v[140:141], v[94:95]
	s_nop 0
	v_pk_fma_f32 v[94:95], v[60:61], v[142:143], v[94:95]
	s_nop 0
	v_pk_fma_f32 v[94:95], v[62:63], v[144:145], v[94:95]
	s_nop 0
	v_pk_fma_f32 v[94:95], v[64:65], v[146:147], v[94:95]
	s_nop 0
	v_pk_fma_f32 v[94:95], v[66:67], v[150:151], v[94:95]
	s_nop 0
	v_pk_fma_f32 v[94:95], v[68:69], v[152:153], v[94:95]
	s_nop 0
	v_pk_fma_f32 v[94:95], v[70:71], v[156:157], v[94:95]
	s_nop 0
	v_pk_fma_f32 v[94:95], v[72:73], v[158:159], v[94:95]
	s_waitcnt lgkmcnt(0)
	v_pk_mul_f32 v[160:161], v[94:95], v[94:95]
	v_mov_b32_e32 v162, v94
	v_mov_b32_e32 v163, v160
	v_mov_b32_e32 v160, v95
	v_pk_add_f32 v[160:161], v[162:163], v[160:161]
	s_nop 1
	v_add_f32_dpp v160, v160, v160 quad_perm:[1,0,3,2] row_mask:0xf bank_mask:0xf
	v_add_f32_dpp v161, v161, v161 quad_perm:[1,0,3,2] row_mask:0xf bank_mask:0xf
	s_waitcnt lgkmcnt(0)
	s_nop 0
	s_nop 1
	v_add_f32_dpp v160, v160, v160 quad_perm:[2,3,0,1] row_mask:0xf bank_mask:0xf
	v_add_f32_dpp v161, v161, v161 quad_perm:[2,3,0,1] row_mask:0xf bank_mask:0xf
	s_waitcnt lgkmcnt(0)
	s_nop 0
	s_nop 1
	v_add_f32_dpp v160, v160, v160 row_half_mirror row_mask:0xf bank_mask:0xf
	v_add_f32_dpp v161, v161, v161 row_half_mirror row_mask:0xf bank_mask:0xf
	s_waitcnt lgkmcnt(0)
	s_nop 0
	s_nop 1
	v_add_f32_dpp v160, v160, v160 row_mirror row_mask:0xf bank_mask:0xf
	v_add_f32_dpp v161, v161, v161 row_mirror row_mask:0xf bank_mask:0xf
	s_waitcnt lgkmcnt(0)
	s_nop 0
	v_mov_b32_e32 v162, v160
	v_mov_b32_e32 v163, v161
	s_nop 1
	v_permlane16_swap_b32_e32 v162, v160
	v_permlane16_swap_b32_e32 v163, v161
	s_nop 1
	s_waitcnt lgkmcnt(0)
	v_pk_add_f32 v[160:161], v[160:161], v[162:163]
	v_mov_b32_e32 v162, v160
	v_mov_b32_e32 v163, v161
	s_nop 1
	v_permlane32_swap_b32_e32 v162, v160
	v_permlane32_swap_b32_e32 v163, v161
	s_nop 1
	s_and_saveexec_b64 s[16:17], s[42:43]
	s_cbranch_execz .LBB0_479
	s_add_i32 s18, s15, 0
	s_add_i32 s18, s18, 0x1f020
	s_waitcnt lgkmcnt(0)
	v_pk_add_f32 v[160:161], v[160:161], v[162:163]
	v_mov_b32_e32 v154, s18
	ds_write_b64 v154, v[160:161]
.LBB0_479:
	s_or_b64 exec, exec, s[16:17]
	v_pk_fma_f32 v[114:115], v[4:5], v[114:115], v[74:75]
	v_lshlrev_b32_e32 v154, 16, v155
	v_pk_fma_f32 v[114:115], v[6:7], v[86:87], v[114:115]
	v_and_b32_e32 v155, 0xffff0000, v155
	v_pk_fma_f32 v[114:115], v[8:9], v[88:89], v[114:115]
	s_nop 0
	v_pk_fma_f32 v[114:115], v[10:11], v[96:97], v[114:115]
	s_nop 0
	v_pk_fma_f32 v[114:115], v[12:13], v[98:99], v[114:115]
	s_nop 0
	v_pk_fma_f32 v[114:115], v[14:15], v[100:101], v[114:115]
	s_nop 0
	v_pk_fma_f32 v[114:115], v[16:17], v[102:103], v[114:115]
	s_nop 0
	v_pk_fma_f32 v[114:115], v[18:19], v[104:105], v[114:115]
	s_nop 0
	v_pk_fma_f32 v[114:115], v[28:29], v[106:107], v[114:115]
	s_nop 0
	v_pk_fma_f32 v[114:115], v[30:31], v[108:109], v[114:115]
	s_nop 0
	v_pk_fma_f32 v[114:115], v[32:33], v[110:111], v[114:115]
	s_nop 0
	v_pk_fma_f32 v[114:115], v[34:35], v[116:117], v[114:115]
	s_nop 0
	v_pk_fma_f32 v[114:115], v[36:37], v[118:119], v[114:115]
	s_nop 0
	v_pk_fma_f32 v[114:115], v[38:39], v[120:121], v[114:115]
	s_nop 0
	v_pk_fma_f32 v[114:115], v[40:41], v[122:123], v[114:115]
	s_nop 0
	v_pk_fma_f32 v[114:115], v[42:43], v[124:125], v[114:115]
	s_nop 0
	v_pk_fma_f32 v[114:115], v[44:45], v[126:127], v[114:115]
	s_nop 0
	v_pk_fma_f32 v[114:115], v[46:47], v[128:129], v[114:115]
	s_nop 0
	v_pk_fma_f32 v[114:115], v[48:49], v[130:131], v[114:115]
	s_nop 0
	v_pk_fma_f32 v[114:115], v[50:51], v[134:135], v[114:115]
	s_nop 0
	v_pk_fma_f32 v[114:115], v[52:53], v[136:137], v[114:115]
	s_nop 0
	v_pk_fma_f32 v[114:115], v[54:55], v[138:139], v[114:115]
	s_nop 0
	v_pk_fma_f32 v[114:115], v[56:57], v[140:141], v[114:115]
	s_nop 0
	v_pk_fma_f32 v[114:115], v[58:59], v[142:143], v[114:115]
	s_nop 0
	v_pk_fma_f32 v[114:115], v[60:61], v[144:145], v[114:115]
	s_nop 0
	v_pk_fma_f32 v[114:115], v[62:63], v[146:147], v[114:115]
	s_nop 0
	v_pk_fma_f32 v[114:115], v[64:65], v[150:151], v[114:115]
	s_nop 0
	v_pk_fma_f32 v[114:115], v[66:67], v[152:153], v[114:115]
	s_nop 0
	v_pk_fma_f32 v[114:115], v[68:69], v[156:157], v[114:115]
	s_nop 0
	v_pk_fma_f32 v[114:115], v[70:71], v[158:159], v[114:115]
	s_nop 0
	v_pk_fma_f32 v[114:115], v[72:73], v[154:155], v[114:115]
	s_nop 0
	v_pk_mul_f32 v[160:161], v[114:115], v[114:115]
	s_waitcnt lgkmcnt(0)
	v_mov_b32_e32 v162, v114
	s_waitcnt lgkmcnt(0)
	v_mov_b32_e32 v163, v160
	v_mov_b32_e32 v160, v115
	v_pk_add_f32 v[160:161], v[162:163], v[160:161]
	s_nop 1
	v_add_f32_dpp v160, v160, v160 quad_perm:[1,0,3,2] row_mask:0xf bank_mask:0xf
	v_add_f32_dpp v161, v161, v161 quad_perm:[1,0,3,2] row_mask:0xf bank_mask:0xf
	s_waitcnt lgkmcnt(0)
	s_nop 0
	s_nop 1
	v_add_f32_dpp v160, v160, v160 quad_perm:[2,3,0,1] row_mask:0xf bank_mask:0xf
	v_add_f32_dpp v161, v161, v161 quad_perm:[2,3,0,1] row_mask:0xf bank_mask:0xf
	s_waitcnt lgkmcnt(0)
	s_nop 0
	s_nop 1
	v_add_f32_dpp v160, v160, v160 row_half_mirror row_mask:0xf bank_mask:0xf
	v_add_f32_dpp v161, v161, v161 row_half_mirror row_mask:0xf bank_mask:0xf
	s_waitcnt lgkmcnt(0)
	s_nop 0
	s_nop 1
	v_add_f32_dpp v160, v160, v160 row_mirror row_mask:0xf bank_mask:0xf
	v_add_f32_dpp v161, v161, v161 row_mirror row_mask:0xf bank_mask:0xf
	s_waitcnt lgkmcnt(0)
	s_nop 0
	v_mov_b32_e32 v162, v160
	v_mov_b32_e32 v163, v161
	s_nop 1
	v_permlane16_swap_b32_e32 v162, v160
	v_permlane16_swap_b32_e32 v163, v161
	s_nop 1
	s_waitcnt lgkmcnt(0)
	v_pk_add_f32 v[160:161], v[160:161], v[162:163]
	v_mov_b32_e32 v162, v160
	v_mov_b32_e32 v163, v161
	s_nop 1
	v_permlane32_swap_b32_e32 v162, v160
	v_permlane32_swap_b32_e32 v163, v161
	s_nop 1
	s_and_saveexec_b64 s[16:17], s[42:43]
	s_cbranch_execz .LBB0_481
	s_add_i32 s18, s15, 0
	s_add_i32 s18, s18, 0x1f028
	s_waitcnt lgkmcnt(0)
	v_pk_add_f32 v[160:161], v[160:161], v[162:163]
	v_mov_b32_e32 v162, s18
	ds_write_b64 v162, v[160:161]
.LBB0_481:
	s_or_b64 exec, exec, s[16:17]
	v_pk_fma_f32 v[86:87], v[4:5], v[86:87], v[74:75]
	v_lshlrev_b32_e32 v160, 16, v148
	v_pk_fma_f32 v[86:87], v[6:7], v[88:89], v[86:87]
	v_and_b32_e32 v161, 0xffff0000, v148
	v_pk_fma_f32 v[86:87], v[8:9], v[96:97], v[86:87]
	s_nop 0
	v_pk_fma_f32 v[86:87], v[10:11], v[98:99], v[86:87]
	s_nop 0
	v_pk_fma_f32 v[86:87], v[12:13], v[100:101], v[86:87]
	s_nop 0
	v_pk_fma_f32 v[86:87], v[14:15], v[102:103], v[86:87]
	s_nop 0
	v_pk_fma_f32 v[86:87], v[16:17], v[104:105], v[86:87]
	s_nop 0
	v_pk_fma_f32 v[86:87], v[18:19], v[106:107], v[86:87]
	s_nop 0
	v_pk_fma_f32 v[86:87], v[28:29], v[108:109], v[86:87]
	s_nop 0
	v_pk_fma_f32 v[86:87], v[30:31], v[110:111], v[86:87]
	s_nop 0
	v_pk_fma_f32 v[86:87], v[32:33], v[116:117], v[86:87]
	s_nop 0
	v_pk_fma_f32 v[86:87], v[34:35], v[118:119], v[86:87]
	s_nop 0
	v_pk_fma_f32 v[86:87], v[36:37], v[120:121], v[86:87]
	s_nop 0
	v_pk_fma_f32 v[86:87], v[38:39], v[122:123], v[86:87]
	s_nop 0
	v_pk_fma_f32 v[86:87], v[40:41], v[124:125], v[86:87]
	s_nop 0
	v_pk_fma_f32 v[86:87], v[42:43], v[126:127], v[86:87]
	s_nop 0
	v_pk_fma_f32 v[86:87], v[44:45], v[128:129], v[86:87]
	s_nop 0
	v_pk_fma_f32 v[86:87], v[46:47], v[130:131], v[86:87]
	s_nop 0
	v_pk_fma_f32 v[86:87], v[48:49], v[134:135], v[86:87]
	s_nop 0
	v_pk_fma_f32 v[86:87], v[50:51], v[136:137], v[86:87]
	s_nop 0
	v_pk_fma_f32 v[86:87], v[52:53], v[138:139], v[86:87]
	s_nop 0
	v_pk_fma_f32 v[86:87], v[54:55], v[140:141], v[86:87]
	s_nop 0
	v_pk_fma_f32 v[86:87], v[56:57], v[142:143], v[86:87]
	s_nop 0
	v_pk_fma_f32 v[86:87], v[58:59], v[144:145], v[86:87]
	s_nop 0
	v_pk_fma_f32 v[86:87], v[60:61], v[146:147], v[86:87]
	s_nop 0
	v_pk_fma_f32 v[86:87], v[62:63], v[150:151], v[86:87]
	s_nop 0
	v_pk_fma_f32 v[86:87], v[64:65], v[152:153], v[86:87]
	s_nop 0
	v_pk_fma_f32 v[86:87], v[66:67], v[156:157], v[86:87]
	s_nop 0
	v_pk_fma_f32 v[86:87], v[68:69], v[158:159], v[86:87]
	s_nop 0
	v_pk_fma_f32 v[86:87], v[70:71], v[154:155], v[86:87]
	s_nop 0
	v_pk_fma_f32 v[86:87], v[72:73], v[160:161], v[86:87]
	s_waitcnt lgkmcnt(0)
	v_pk_mul_f32 v[162:163], v[86:87], v[86:87]
	v_mov_b32_e32 v164, v86
	v_mov_b32_e32 v165, v162
	v_mov_b32_e32 v162, v87
	v_pk_add_f32 v[162:163], v[164:165], v[162:163]
	s_nop 1
	v_add_f32_dpp v162, v162, v162 quad_perm:[1,0,3,2] row_mask:0xf bank_mask:0xf
	v_add_f32_dpp v163, v163, v163 quad_perm:[1,0,3,2] row_mask:0xf bank_mask:0xf
	s_waitcnt lgkmcnt(0)
	s_nop 0
	s_nop 1
	v_add_f32_dpp v162, v162, v162 quad_perm:[2,3,0,1] row_mask:0xf bank_mask:0xf
	v_add_f32_dpp v163, v163, v163 quad_perm:[2,3,0,1] row_mask:0xf bank_mask:0xf
	s_waitcnt lgkmcnt(0)
	s_nop 0
	s_nop 1
	v_add_f32_dpp v162, v162, v162 row_half_mirror row_mask:0xf bank_mask:0xf
	v_add_f32_dpp v163, v163, v163 row_half_mirror row_mask:0xf bank_mask:0xf
	s_waitcnt lgkmcnt(0)
	s_nop 0
	s_nop 1
	v_add_f32_dpp v162, v162, v162 row_mirror row_mask:0xf bank_mask:0xf
	v_add_f32_dpp v163, v163, v163 row_mirror row_mask:0xf bank_mask:0xf
	s_waitcnt lgkmcnt(0)
	s_nop 0
	v_mov_b32_e32 v164, v162
	v_mov_b32_e32 v165, v163
	s_nop 1
	v_permlane16_swap_b32_e32 v164, v162
	v_permlane16_swap_b32_e32 v165, v163
	s_nop 1
	s_waitcnt lgkmcnt(0)
	v_pk_add_f32 v[162:163], v[162:163], v[164:165]
	v_mov_b32_e32 v164, v162
	v_mov_b32_e32 v165, v163
	s_nop 1
	v_permlane32_swap_b32_e32 v164, v162
	v_permlane32_swap_b32_e32 v165, v163
	s_nop 1
	s_and_saveexec_b64 s[16:17], s[42:43]
	s_cbranch_execz .LBB0_483
	s_add_i32 s18, s15, 0
	s_add_i32 s18, s18, 0x1f030
	s_waitcnt lgkmcnt(0)
	v_pk_add_f32 v[162:163], v[162:163], v[164:165]
	v_mov_b32_e32 v148, s18
	ds_write_b64 v148, v[162:163]
.LBB0_483:
	s_or_b64 exec, exec, s[16:17]
	v_pk_fma_f32 v[88:89], v[4:5], v[88:89], v[74:75]
	s_nop 0
	v_pk_fma_f32 v[88:89], v[6:7], v[96:97], v[88:89]
	v_lshlrev_b32_e32 v96, 16, v149
	v_pk_fma_f32 v[88:89], v[8:9], v[98:99], v[88:89]
	v_and_b32_e32 v97, 0xffff0000, v149
	v_pk_fma_f32 v[88:89], v[10:11], v[100:101], v[88:89]
	s_nop 0
	v_pk_fma_f32 v[88:89], v[12:13], v[102:103], v[88:89]
	s_nop 0
	v_pk_fma_f32 v[88:89], v[14:15], v[104:105], v[88:89]
	s_nop 0
	v_pk_fma_f32 v[88:89], v[16:17], v[106:107], v[88:89]
	s_nop 0
	v_pk_fma_f32 v[88:89], v[18:19], v[108:109], v[88:89]
	s_nop 0
	v_pk_fma_f32 v[88:89], v[28:29], v[110:111], v[88:89]
	s_nop 0
	v_pk_fma_f32 v[88:89], v[30:31], v[116:117], v[88:89]
	s_nop 0
	v_pk_fma_f32 v[88:89], v[32:33], v[118:119], v[88:89]
	s_nop 0
	v_pk_fma_f32 v[88:89], v[34:35], v[120:121], v[88:89]
	s_nop 0
	v_pk_fma_f32 v[88:89], v[36:37], v[122:123], v[88:89]
	s_nop 0
	v_pk_fma_f32 v[88:89], v[38:39], v[124:125], v[88:89]
	s_nop 0
	v_pk_fma_f32 v[88:89], v[40:41], v[126:127], v[88:89]
	s_nop 0
	v_pk_fma_f32 v[88:89], v[42:43], v[128:129], v[88:89]
	s_nop 0
	v_pk_fma_f32 v[88:89], v[44:45], v[130:131], v[88:89]
	s_nop 0
	v_pk_fma_f32 v[88:89], v[46:47], v[134:135], v[88:89]
	s_nop 0
	v_pk_fma_f32 v[88:89], v[48:49], v[136:137], v[88:89]
	s_nop 0
	v_pk_fma_f32 v[88:89], v[50:51], v[138:139], v[88:89]
	s_nop 0
	v_pk_fma_f32 v[88:89], v[52:53], v[140:141], v[88:89]
	s_nop 0
	v_pk_fma_f32 v[88:89], v[54:55], v[142:143], v[88:89]
	s_nop 0
	v_pk_fma_f32 v[88:89], v[56:57], v[144:145], v[88:89]
	s_nop 0
	v_pk_fma_f32 v[88:89], v[58:59], v[146:147], v[88:89]
	s_nop 0
	v_pk_fma_f32 v[88:89], v[60:61], v[150:151], v[88:89]
	s_nop 0
	v_pk_fma_f32 v[88:89], v[62:63], v[152:153], v[88:89]
	s_nop 0
	v_pk_fma_f32 v[88:89], v[64:65], v[156:157], v[88:89]
	s_nop 0
	v_pk_fma_f32 v[88:89], v[66:67], v[158:159], v[88:89]
	s_nop 0
	v_pk_fma_f32 v[88:89], v[68:69], v[154:155], v[88:89]
	s_nop 0
	v_pk_fma_f32 v[88:89], v[70:71], v[160:161], v[88:89]
	s_nop 0
	v_pk_fma_f32 v[88:89], v[72:73], v[96:97], v[88:89]
	s_nop 0
	v_pk_mul_f32 v[96:97], v[88:89], v[88:89]
	v_mov_b32_e32 v98, v88
	v_mov_b32_e32 v99, v96
	v_mov_b32_e32 v96, v89
	v_pk_add_f32 v[96:97], v[98:99], v[96:97]
	s_nop 1
	v_add_f32_dpp v96, v96, v96 quad_perm:[1,0,3,2] row_mask:0xf bank_mask:0xf
	v_add_f32_dpp v97, v97, v97 quad_perm:[1,0,3,2] row_mask:0xf bank_mask:0xf
	s_waitcnt lgkmcnt(0)
	s_nop 0
	s_nop 1
	v_add_f32_dpp v96, v96, v96 quad_perm:[2,3,0,1] row_mask:0xf bank_mask:0xf
	v_add_f32_dpp v97, v97, v97 quad_perm:[2,3,0,1] row_mask:0xf bank_mask:0xf
	s_waitcnt lgkmcnt(0)
	s_nop 0
	s_nop 1
	v_add_f32_dpp v96, v96, v96 row_half_mirror row_mask:0xf bank_mask:0xf
	v_add_f32_dpp v97, v97, v97 row_half_mirror row_mask:0xf bank_mask:0xf
	s_waitcnt lgkmcnt(0)
	s_nop 0
	s_nop 1
	v_add_f32_dpp v96, v96, v96 row_mirror row_mask:0xf bank_mask:0xf
	v_add_f32_dpp v97, v97, v97 row_mirror row_mask:0xf bank_mask:0xf
	s_waitcnt lgkmcnt(0)
	s_nop 0
	v_mov_b32_e32 v98, v96
	v_mov_b32_e32 v99, v97
	s_nop 1
	v_permlane16_swap_b32_e32 v98, v96
	v_permlane16_swap_b32_e32 v99, v97
	s_nop 1
	s_waitcnt lgkmcnt(0)
	v_pk_add_f32 v[96:97], v[96:97], v[98:99]
	v_mov_b32_e32 v98, v96
	v_mov_b32_e32 v99, v97
	s_nop 1
	v_permlane32_swap_b32_e32 v98, v96
	v_permlane32_swap_b32_e32 v99, v97
	s_nop 1
	s_and_saveexec_b64 s[16:17], s[42:43]
	s_cbranch_execz .LBB0_485
	s_add_i32 s18, s15, 0
	s_add_i32 s18, s18, 0x1f038
	s_waitcnt lgkmcnt(0)
	v_pk_add_f32 v[96:97], v[96:97], v[98:99]
	v_mov_b32_e32 v98, s18
	ds_write_b64 v98, v[96:97]
.LBB0_485:
	s_or_b64 exec, exec, s[16:17]
	s_waitcnt lgkmcnt(0)
	s_barrier
	s_and_saveexec_b64 s[16:17], s[44:45]
	s_cbranch_execz .LBB0_468
	ds_read2_b64 v[96:99], v166 offset1:8
	ds_read2_b64 v[100:103], v166 offset0:16 offset1:24
	ds_read2_b64 v[104:107], v166 offset0:32 offset1:40
	ds_read2_b64 v[108:111], v166 offset0:48 offset1:56
	s_mov_b32 s18, 0x3a800000
	s_waitcnt lgkmcnt(0)
	v_pk_add_f32 v[96:97], v[96:97], 0 op_sel_hi:[1,0]
	s_nop 0
	v_pk_add_f32 v[96:97], v[96:97], v[98:99]
	s_waitcnt lgkmcnt(0)
	v_pk_add_f32 v[96:97], v[96:97], v[100:101]
	s_nop 0
	v_pk_add_f32 v[96:97], v[96:97], v[102:103]
	s_waitcnt lgkmcnt(0)
	v_pk_add_f32 v[96:97], v[96:97], v[104:105]
	s_nop 0
	v_pk_add_f32 v[96:97], v[96:97], v[106:107]
	s_waitcnt lgkmcnt(0)
	v_pk_add_f32 v[96:97], v[96:97], v[108:109]
	s_nop 0
	v_pk_add_f32 v[96:97], v[96:97], v[110:111]
	s_nop 0
	v_pk_mul_f32 v[96:97], v[96:97], s[18:19] op_sel_hi:[1,0]
	s_nop 0
	v_fma_f32 v97, -v96, v96, v97
	v_max_f32_e32 v97, 0, v97
	v_add_f32_e32 v97, 0x358637bd, v97
	v_mul_f32_e32 v98, 0x4f800000, v97
	v_cmp_gt_f32_e32 vcc, s91, v97
	s_nop 1
	v_cndmask_b32_e32 v97, v97, v98, vcc
	v_sqrt_f32_e32 v98, v97
	s_nop 0
	v_add_u32_e32 v99, -1, v98
	v_add_u32_e32 v100, 1, v98
	v_fma_f32 v101, -v99, v98, v97
	v_fma_f32 v102, -v100, v98, v97
	v_cmp_ge_f32_e64 s[48:49], 0, v101
	s_nop 1
	v_cndmask_b32_e64 v98, v98, v99, s[48:49]
	v_cmp_lt_f32_e64 s[48:49], 0, v102
	s_nop 1
	v_cndmask_b32_e64 v98, v98, v100, s[48:49]
	v_mul_f32_e32 v99, 0x37800000, v98
	v_cndmask_b32_e32 v98, v98, v99, vcc
	v_cmp_class_f32_e32 vcc, v97, v202
	s_nop 1
	v_cndmask_b32_e32 v97, v98, v97, vcc
	v_div_scale_f32 v98, s[18:19], v97, v97, 1.0
	v_rcp_f32_e32 v99, v98
	s_nop 0
	v_fma_f32 v100, -v98, v99, 1.0
	v_fmac_f32_e32 v99, v100, v99
	v_div_scale_f32 v100, vcc, 1.0, v97, 1.0
	v_mul_f32_e32 v101, v100, v99
	v_fma_f32 v102, -v98, v101, v100
	v_fmac_f32_e32 v101, v102, v99
	v_fma_f32 v98, -v98, v101, v100
	v_div_fmas_f32 v98, v98, v99, v101
	v_div_fixup_f32 v97, v98, v97, 1.0
	ds_write_b64 v167, v[96:97]
	s_branch .LBB0_468

.LBB0_497:
	v_add_u32_e32 v80, 0xffff0000, v177
	v_add_u32_e32 v81, 0xffff0800, v177
	v_add_u32_e32 v82, 0xffff1000, v177
	v_add_u32_e32 v83, 0xffff1800, v177
	v_add_u32_e32 v86, 0xffff2000, v177
	v_add_u32_e32 v87, 0xffff2800, v177
	v_add_u32_e32 v88, 0xffff3000, v177
	v_add_u32_e32 v89, 0xffff3800, v177
	ds_read_b32 v90, v80
	ds_read_b32 v91, v81
	ds_read_b32 v82, v82
	ds_read_b32 v83, v83
	ds_read_b32 v86, v86
	ds_read_b32 v87, v87
	ds_read_b32 v88, v88
	ds_read_b32 v89, v89
	s_waitcnt lgkmcnt(0)
	v_lshlrev_b32_e32 v80, 16, v90
	v_and_b32_e32 v81, 0xffff0000, v90
	v_pk_fma_f32 v[80:81], v[4:5], v[80:81], v[74:75]
	s_waitcnt lgkmcnt(0)
	v_lshlrev_b32_e32 v104, 16, v91
	v_and_b32_e32 v105, 0xffff0000, v91
	v_pk_fma_f32 v[80:81], v[6:7], v[104:105], v[80:81]
	s_waitcnt lgkmcnt(0)
	v_lshlrev_b32_e32 v116, 16, v82
	v_and_b32_e32 v117, 0xffff0000, v82
	v_pk_fma_f32 v[80:81], v[8:9], v[116:117], v[80:81]
	s_waitcnt lgkmcnt(0)
	v_lshlrev_b32_e32 v134, 16, v83
	v_and_b32_e32 v135, 0xffff0000, v83
	v_pk_fma_f32 v[80:81], v[10:11], v[134:135], v[80:81]
	s_waitcnt lgkmcnt(0)
	v_lshlrev_b32_e32 v138, 16, v86
	v_and_b32_e32 v139, 0xffff0000, v86
	v_pk_fma_f32 v[80:81], v[12:13], v[138:139], v[80:81]
	s_waitcnt lgkmcnt(0)
	v_lshlrev_b32_e32 v144, 16, v87
	v_and_b32_e32 v145, 0xffff0000, v87
	v_pk_fma_f32 v[80:81], v[14:15], v[144:145], v[80:81]
	s_waitcnt lgkmcnt(0)
	v_lshlrev_b32_e32 v142, 16, v88
	v_and_b32_e32 v143, 0xffff0000, v88
	v_pk_fma_f32 v[80:81], v[16:17], v[142:143], v[80:81]
	s_waitcnt lgkmcnt(0)
	v_lshlrev_b32_e32 v136, 16, v89
	v_and_b32_e32 v137, 0xffff0000, v89
	v_add_u32_e32 v82, 0xffff4000, v177
	v_add_u32_e32 v83, 0xffff4800, v177
	v_add_u32_e32 v86, 0xffff5000, v177
	v_pk_fma_f32 v[80:81], v[18:19], v[136:137], v[80:81]
	v_add_u32_e32 v87, 0xffff5800, v177
	v_add_u32_e32 v88, 0xffff6000, v177
	v_add_u32_e32 v89, 0xffff6800, v177
	v_add_u32_e32 v90, 0xffff7000, v177
	v_add_u32_e32 v91, 0xffff7800, v177
	ds_read_b32 v82, v82
	ds_read_b32 v83, v83
	ds_read_b32 v86, v86
	ds_read_b32 v92, v87
	ds_read_b32 v93, v88
	ds_read_b32 v94, v89
	ds_read_b32 v95, v90
	ds_read_b32 v96, v91
	s_waitcnt lgkmcnt(0)
	v_lshlrev_b32_e32 v132, 16, v82
	v_and_b32_e32 v133, 0xffff0000, v82
	v_pk_fma_f32 v[80:81], v[28:29], v[132:133], v[80:81]
	s_waitcnt lgkmcnt(0)
	v_lshlrev_b32_e32 v110, 16, v83
	v_and_b32_e32 v111, 0xffff0000, v83
	v_pk_fma_f32 v[82:83], v[30:31], v[110:111], v[80:81]
	s_waitcnt lgkmcnt(0)
	v_lshlrev_b32_e32 v80, 16, v86
	v_and_b32_e32 v81, 0xffff0000, v86
	v_pk_fma_f32 v[86:87], v[32:33], v[80:81], v[82:83]
	s_waitcnt lgkmcnt(0)
	v_lshlrev_b32_e32 v82, 16, v92
	v_and_b32_e32 v83, 0xffff0000, v92
	v_pk_fma_f32 v[88:89], v[34:35], v[82:83], v[86:87]
	s_waitcnt lgkmcnt(0)
	v_lshlrev_b32_e32 v86, 16, v93
	v_and_b32_e32 v87, 0xffff0000, v93
	v_pk_fma_f32 v[90:91], v[36:37], v[86:87], v[88:89]
	s_waitcnt lgkmcnt(0)
	v_lshlrev_b32_e32 v88, 16, v94
	v_and_b32_e32 v89, 0xffff0000, v94
	v_pk_fma_f32 v[92:93], v[38:39], v[88:89], v[90:91]
	s_waitcnt lgkmcnt(0)
	v_lshlrev_b32_e32 v90, 16, v95
	v_and_b32_e32 v91, 0xffff0000, v95
	v_pk_fma_f32 v[94:95], v[40:41], v[90:91], v[92:93]
	s_waitcnt lgkmcnt(0)
	v_lshlrev_b32_e32 v92, 16, v96
	v_and_b32_e32 v93, 0xffff0000, v96
	v_add_u32_e32 v96, 0xffff8000, v177
	v_add_u32_e32 v97, 0xffff8800, v177
	v_pk_fma_f32 v[94:95], v[42:43], v[92:93], v[94:95]
	v_add_u32_e32 v98, 0xffff9000, v177
	v_add_u32_e32 v99, 0xffff9800, v177
	v_add_u32_e32 v100, 0xffffa000, v177
	v_add_u32_e32 v101, 0xffffa800, v177
	v_add_u32_e32 v102, 0xffffb000, v177
	v_add_u32_e32 v103, 0xffffb800, v177
	ds_read_b32 v106, v96
	ds_read_b32 v107, v97
	ds_read_b32 v108, v98
	ds_read_b32 v109, v99
	ds_read_b32 v112, v100
	ds_read_b32 v113, v101
	ds_read_b32 v114, v102
	ds_read_b32 v115, v103
	s_waitcnt lgkmcnt(0)
	v_lshlrev_b32_e32 v96, 16, v106
	v_and_b32_e32 v97, 0xffff0000, v106
	v_pk_fma_f32 v[94:95], v[44:45], v[96:97], v[94:95]
	s_waitcnt lgkmcnt(0)
	v_lshlrev_b32_e32 v98, 16, v107
	v_and_b32_e32 v99, 0xffff0000, v107
	v_pk_fma_f32 v[94:95], v[46:47], v[98:99], v[94:95]
	s_waitcnt lgkmcnt(0)
	v_lshlrev_b32_e32 v100, 16, v108
	v_and_b32_e32 v101, 0xffff0000, v108
	v_pk_fma_f32 v[94:95], v[48:49], v[100:101], v[94:95]
	s_waitcnt lgkmcnt(0)
	v_lshlrev_b32_e32 v102, 16, v109
	v_and_b32_e32 v103, 0xffff0000, v109
	v_pk_fma_f32 v[94:95], v[50:51], v[102:103], v[94:95]
	s_waitcnt lgkmcnt(0)
	v_lshlrev_b32_e32 v106, 16, v112
	v_and_b32_e32 v107, 0xffff0000, v112
	v_pk_fma_f32 v[94:95], v[52:53], v[106:107], v[94:95]
	s_waitcnt lgkmcnt(0)
	v_lshlrev_b32_e32 v108, 16, v113
	v_and_b32_e32 v109, 0xffff0000, v113
	v_pk_fma_f32 v[94:95], v[54:55], v[108:109], v[94:95]
	s_waitcnt lgkmcnt(0)
	v_lshlrev_b32_e32 v112, 16, v114
	v_and_b32_e32 v113, 0xffff0000, v114
	v_pk_fma_f32 v[94:95], v[56:57], v[112:113], v[94:95]
	s_waitcnt lgkmcnt(0)
	v_lshlrev_b32_e32 v114, 16, v115
	v_and_b32_e32 v115, 0xffff0000, v115
	v_add_u32_e32 v118, 0xffffc000, v177
	v_add_u32_e32 v119, 0xffffc800, v177
	v_pk_fma_f32 v[94:95], v[58:59], v[114:115], v[94:95]
	v_add_u32_e32 v120, 0xffffd000, v177
	v_add_u32_e32 v121, 0xffffd800, v177
	v_add_u32_e32 v122, 0xffffe000, v177
	v_add_u32_e32 v123, 0xffffe800, v177
	v_add_u32_e32 v124, 0xfffff000, v177
	v_add_u32_e32 v125, 0xfffff800, v177
	ds_read_b32 v126, v118
	ds_read_b32 v127, v119
	ds_read_b32 v128, v120
	ds_read_b32 v129, v121
	ds_read_b32 v130, v122
	ds_read_b32 v131, v123
	ds_read_b32 v140, v124
	ds_read_b32 v154, v125
	s_waitcnt lgkmcnt(0)
	v_lshlrev_b32_e32 v118, 16, v126
	v_and_b32_e32 v119, 0xffff0000, v126
	v_pk_fma_f32 v[94:95], v[60:61], v[118:119], v[94:95]
	s_waitcnt lgkmcnt(0)
	v_lshlrev_b32_e32 v120, 16, v127
	v_and_b32_e32 v121, 0xffff0000, v127
	v_pk_fma_f32 v[94:95], v[62:63], v[120:121], v[94:95]
	s_waitcnt lgkmcnt(0)
	v_lshlrev_b32_e32 v122, 16, v128
	v_and_b32_e32 v123, 0xffff0000, v128
	v_pk_fma_f32 v[94:95], v[64:65], v[122:123], v[94:95]
	s_waitcnt lgkmcnt(0)
	v_lshlrev_b32_e32 v124, 16, v129
	v_and_b32_e32 v125, 0xffff0000, v129
	v_pk_fma_f32 v[94:95], v[66:67], v[124:125], v[94:95]
	s_waitcnt lgkmcnt(0)
	v_lshlrev_b32_e32 v126, 16, v130
	v_and_b32_e32 v127, 0xffff0000, v130
	v_pk_fma_f32 v[94:95], v[68:69], v[126:127], v[94:95]
	s_waitcnt lgkmcnt(0)
	v_lshlrev_b32_e32 v128, 16, v131
	v_and_b32_e32 v129, 0xffff0000, v131
	v_pk_fma_f32 v[94:95], v[70:71], v[128:129], v[94:95]
	s_waitcnt lgkmcnt(0)
	v_lshlrev_b32_e32 v130, 16, v140
	v_and_b32_e32 v131, 0xffff0000, v140
	v_pk_fma_f32 v[94:95], v[72:73], v[130:131], v[94:95]
	ds_read2st64_b32 v[150:151], v177 offset1:8
	v_pk_mul_f32 v[140:141], v[94:95], v[94:95]
	v_mov_b32_e32 v146, v94
	v_mov_b32_e32 v147, v140
	v_mov_b32_e32 v140, v95
	v_pk_add_f32 v[140:141], v[146:147], v[140:141]
	s_nop 1
	v_add_f32_dpp v140, v140, v140 quad_perm:[1,0,3,2] row_mask:0xf bank_mask:0xf
	v_add_f32_dpp v141, v141, v141 quad_perm:[1,0,3,2] row_mask:0xf bank_mask:0xf
	s_waitcnt lgkmcnt(0)
	s_nop 0
	s_nop 1
	v_add_f32_dpp v140, v140, v140 quad_perm:[2,3,0,1] row_mask:0xf bank_mask:0xf
	v_add_f32_dpp v141, v141, v141 quad_perm:[2,3,0,1] row_mask:0xf bank_mask:0xf
	s_waitcnt lgkmcnt(0)
	s_nop 0
	s_nop 1
	v_add_f32_dpp v140, v140, v140 row_half_mirror row_mask:0xf bank_mask:0xf
	v_add_f32_dpp v141, v141, v141 row_half_mirror row_mask:0xf bank_mask:0xf
	s_waitcnt lgkmcnt(0)
	s_nop 0
	s_nop 1
	v_add_f32_dpp v140, v140, v140 row_mirror row_mask:0xf bank_mask:0xf
	v_add_f32_dpp v141, v141, v141 row_mirror row_mask:0xf bank_mask:0xf
	s_waitcnt lgkmcnt(0)
	s_nop 0
	v_mov_b32_e32 v148, v140
	v_mov_b32_e32 v149, v141
	s_nop 1
	v_permlane16_swap_b32_e32 v148, v140
	v_permlane16_swap_b32_e32 v149, v141
	s_nop 1
	ds_read2st64_b32 v[156:157], v177 offset0:16 offset1:24
	ds_read2st64_b32 v[152:153], v177 offset0:32 offset1:40
	ds_read2st64_b32 v[146:147], v177 offset0:48 offset1:56
	ds_read_b32 v178, v177 offset:16384
	s_waitcnt lgkmcnt(0)
	v_pk_add_f32 v[140:141], v[140:141], v[148:149]
	v_mov_b32_e32 v148, v140
	v_mov_b32_e32 v149, v141
	s_nop 1
	v_permlane32_swap_b32_e32 v148, v140
	v_permlane32_swap_b32_e32 v149, v141
	s_nop 1
	s_and_saveexec_b64 s[12:13], s[42:43]
	s_cbranch_execz .LBB0_499
	s_add_i32 s17, s16, 0
	s_add_i32 s17, s17, 0x25000
	s_waitcnt lgkmcnt(0)
	v_pk_add_f32 v[140:141], v[140:141], v[148:149]
	v_mov_b32_e32 v148, s17
	ds_write_b64 v148, v[140:141]
.LBB0_499:
	s_or_b64 exec, exec, s[12:13]
	v_pk_fma_f32 v[104:105], v[4:5], v[104:105], v[74:75]
	v_lshlrev_b32_e32 v140, 16, v154
	v_pk_fma_f32 v[104:105], v[6:7], v[116:117], v[104:105]
	v_and_b32_e32 v141, 0xffff0000, v154
	v_pk_fma_f32 v[104:105], v[8:9], v[134:135], v[104:105]
	s_nop 0
	v_pk_fma_f32 v[104:105], v[10:11], v[138:139], v[104:105]
	s_nop 0
	v_pk_fma_f32 v[104:105], v[12:13], v[144:145], v[104:105]
	s_nop 0
	v_pk_fma_f32 v[104:105], v[14:15], v[142:143], v[104:105]
	s_nop 0
	v_pk_fma_f32 v[104:105], v[16:17], v[136:137], v[104:105]
	s_nop 0
	v_pk_fma_f32 v[104:105], v[18:19], v[132:133], v[104:105]
	s_nop 0
	v_pk_fma_f32 v[104:105], v[28:29], v[110:111], v[104:105]
	s_nop 0
	v_pk_fma_f32 v[104:105], v[30:31], v[80:81], v[104:105]
	s_nop 0
	v_pk_fma_f32 v[104:105], v[32:33], v[82:83], v[104:105]
	s_nop 0
	v_pk_fma_f32 v[104:105], v[34:35], v[86:87], v[104:105]
	s_nop 0
	v_pk_fma_f32 v[104:105], v[36:37], v[88:89], v[104:105]
	s_nop 0
	v_pk_fma_f32 v[104:105], v[38:39], v[90:91], v[104:105]
	s_nop 0
	v_pk_fma_f32 v[104:105], v[40:41], v[92:93], v[104:105]
	s_nop 0
	v_pk_fma_f32 v[104:105], v[42:43], v[96:97], v[104:105]
	s_nop 0
	v_pk_fma_f32 v[104:105], v[44:45], v[98:99], v[104:105]
	s_nop 0
	v_pk_fma_f32 v[104:105], v[46:47], v[100:101], v[104:105]
	s_nop 0
	v_pk_fma_f32 v[104:105], v[48:49], v[102:103], v[104:105]
	s_nop 0
	v_pk_fma_f32 v[104:105], v[50:51], v[106:107], v[104:105]
	s_nop 0
	v_pk_fma_f32 v[104:105], v[52:53], v[108:109], v[104:105]
	s_nop 0
	v_pk_fma_f32 v[104:105], v[54:55], v[112:113], v[104:105]
	s_nop 0
	v_pk_fma_f32 v[104:105], v[56:57], v[114:115], v[104:105]
	s_nop 0
	v_pk_fma_f32 v[104:105], v[58:59], v[118:119], v[104:105]
	s_nop 0
	v_pk_fma_f32 v[104:105], v[60:61], v[120:121], v[104:105]
	s_nop 0
	v_pk_fma_f32 v[104:105], v[62:63], v[122:123], v[104:105]
	s_nop 0
	v_pk_fma_f32 v[104:105], v[64:65], v[124:125], v[104:105]
	s_nop 0
	v_pk_fma_f32 v[104:105], v[66:67], v[126:127], v[104:105]
	s_nop 0
	v_pk_fma_f32 v[104:105], v[68:69], v[128:129], v[104:105]
	s_nop 0
	v_pk_fma_f32 v[104:105], v[70:71], v[130:131], v[104:105]
	s_nop 0
	v_pk_fma_f32 v[104:105], v[72:73], v[140:141], v[104:105]
	s_waitcnt lgkmcnt(0)
	v_pk_mul_f32 v[148:149], v[104:105], v[104:105]
	v_mov_b32_e32 v154, v104
	v_mov_b32_e32 v155, v148
	v_mov_b32_e32 v148, v105
	v_pk_add_f32 v[148:149], v[154:155], v[148:149]
	s_nop 1
	v_add_f32_dpp v148, v148, v148 quad_perm:[1,0,3,2] row_mask:0xf bank_mask:0xf
	v_add_f32_dpp v149, v149, v149 quad_perm:[1,0,3,2] row_mask:0xf bank_mask:0xf
	s_waitcnt lgkmcnt(0)
	s_nop 0
	s_nop 1
	v_add_f32_dpp v148, v148, v148 quad_perm:[2,3,0,1] row_mask:0xf bank_mask:0xf
	v_add_f32_dpp v149, v149, v149 quad_perm:[2,3,0,1] row_mask:0xf bank_mask:0xf
	s_waitcnt lgkmcnt(0)
	s_nop 0
	s_nop 1
	v_add_f32_dpp v148, v148, v148 row_half_mirror row_mask:0xf bank_mask:0xf
	v_add_f32_dpp v149, v149, v149 row_half_mirror row_mask:0xf bank_mask:0xf
	s_waitcnt lgkmcnt(0)
	s_nop 0
	s_nop 1
	v_add_f32_dpp v148, v148, v148 row_mirror row_mask:0xf bank_mask:0xf
	v_add_f32_dpp v149, v149, v149 row_mirror row_mask:0xf bank_mask:0xf
	s_waitcnt lgkmcnt(0)
	s_nop 0
	v_mov_b32_e32 v154, v148
	v_mov_b32_e32 v155, v149
	s_nop 1
	v_permlane16_swap_b32_e32 v154, v148
	v_permlane16_swap_b32_e32 v155, v149
	s_nop 1
	s_waitcnt lgkmcnt(0)
	v_pk_add_f32 v[148:149], v[148:149], v[154:155]
	v_mov_b32_e32 v154, v148
	v_mov_b32_e32 v155, v149
	s_nop 1
	v_permlane32_swap_b32_e32 v154, v148
	v_permlane32_swap_b32_e32 v155, v149
	s_nop 1
	s_and_saveexec_b64 s[12:13], s[42:43]
	s_cbranch_execz .LBB0_501
	s_add_i32 s17, s16, 0
	s_add_i32 s17, s17, 0x25008
	s_waitcnt lgkmcnt(0)
	v_pk_add_f32 v[148:149], v[148:149], v[154:155]
	v_mov_b32_e32 v154, s17
	ds_write_b64 v154, v[148:149]
.LBB0_501:
	s_or_b64 exec, exec, s[12:13]
	v_pk_fma_f32 v[116:117], v[4:5], v[116:117], v[74:75]
	v_lshlrev_b32_e32 v148, 16, v150
	v_pk_fma_f32 v[116:117], v[6:7], v[134:135], v[116:117]
	v_and_b32_e32 v149, 0xffff0000, v150
	v_pk_fma_f32 v[116:117], v[8:9], v[138:139], v[116:117]
	s_nop 0
	v_pk_fma_f32 v[116:117], v[10:11], v[144:145], v[116:117]
	s_nop 0
	v_pk_fma_f32 v[116:117], v[12:13], v[142:143], v[116:117]
	s_nop 0
	v_pk_fma_f32 v[116:117], v[14:15], v[136:137], v[116:117]
	s_nop 0
	v_pk_fma_f32 v[116:117], v[16:17], v[132:133], v[116:117]
	s_nop 0
	v_pk_fma_f32 v[116:117], v[18:19], v[110:111], v[116:117]
	s_nop 0
	v_pk_fma_f32 v[116:117], v[28:29], v[80:81], v[116:117]
	s_nop 0
	v_pk_fma_f32 v[116:117], v[30:31], v[82:83], v[116:117]
	s_nop 0
	v_pk_fma_f32 v[116:117], v[32:33], v[86:87], v[116:117]
	s_nop 0
	v_pk_fma_f32 v[116:117], v[34:35], v[88:89], v[116:117]
	s_nop 0
	v_pk_fma_f32 v[116:117], v[36:37], v[90:91], v[116:117]
	s_nop 0
	v_pk_fma_f32 v[116:117], v[38:39], v[92:93], v[116:117]
	s_nop 0
	v_pk_fma_f32 v[116:117], v[40:41], v[96:97], v[116:117]
	s_nop 0
	v_pk_fma_f32 v[116:117], v[42:43], v[98:99], v[116:117]
	s_nop 0
	v_pk_fma_f32 v[116:117], v[44:45], v[100:101], v[116:117]
	s_nop 0
	v_pk_fma_f32 v[116:117], v[46:47], v[102:103], v[116:117]
	s_nop 0
	v_pk_fma_f32 v[116:117], v[48:49], v[106:107], v[116:117]
	s_nop 0
	v_pk_fma_f32 v[116:117], v[50:51], v[108:109], v[116:117]
	s_nop 0
	v_pk_fma_f32 v[116:117], v[52:53], v[112:113], v[116:117]
	s_nop 0
	v_pk_fma_f32 v[116:117], v[54:55], v[114:115], v[116:117]
	s_nop 0
	v_pk_fma_f32 v[116:117], v[56:57], v[118:119], v[116:117]
	s_nop 0
	v_pk_fma_f32 v[116:117], v[58:59], v[120:121], v[116:117]
	s_nop 0
	v_pk_fma_f32 v[116:117], v[60:61], v[122:123], v[116:117]
	s_nop 0
	v_pk_fma_f32 v[116:117], v[62:63], v[124:125], v[116:117]
	s_nop 0
	v_pk_fma_f32 v[116:117], v[64:65], v[126:127], v[116:117]
	s_nop 0
	v_pk_fma_f32 v[116:117], v[66:67], v[128:129], v[116:117]
	s_nop 0
	v_pk_fma_f32 v[116:117], v[68:69], v[130:131], v[116:117]
	s_nop 0
	v_pk_fma_f32 v[116:117], v[70:71], v[140:141], v[116:117]
	s_nop 0
	v_pk_fma_f32 v[116:117], v[72:73], v[148:149], v[116:117]
	s_waitcnt lgkmcnt(0)
	v_pk_mul_f32 v[154:155], v[116:117], v[116:117]
	v_mov_b32_e32 v158, v116
	v_mov_b32_e32 v159, v154
	v_mov_b32_e32 v154, v117
	v_pk_add_f32 v[154:155], v[158:159], v[154:155]
	s_nop 1
	v_add_f32_dpp v154, v154, v154 quad_perm:[1,0,3,2] row_mask:0xf bank_mask:0xf
	v_add_f32_dpp v155, v155, v155 quad_perm:[1,0,3,2] row_mask:0xf bank_mask:0xf
	s_waitcnt lgkmcnt(0)
	s_nop 0
	s_nop 1
	v_add_f32_dpp v154, v154, v154 quad_perm:[2,3,0,1] row_mask:0xf bank_mask:0xf
	v_add_f32_dpp v155, v155, v155 quad_perm:[2,3,0,1] row_mask:0xf bank_mask:0xf
	s_waitcnt lgkmcnt(0)
	s_nop 0
	s_nop 1
	v_add_f32_dpp v154, v154, v154 row_half_mirror row_mask:0xf bank_mask:0xf
	v_add_f32_dpp v155, v155, v155 row_half_mirror row_mask:0xf bank_mask:0xf
	s_waitcnt lgkmcnt(0)
	s_nop 0
	s_nop 1
	v_add_f32_dpp v154, v154, v154 row_mirror row_mask:0xf bank_mask:0xf
	v_add_f32_dpp v155, v155, v155 row_mirror row_mask:0xf bank_mask:0xf
	s_waitcnt lgkmcnt(0)
	s_nop 0
	v_mov_b32_e32 v158, v154
	v_mov_b32_e32 v159, v155
	s_nop 1
	v_permlane16_swap_b32_e32 v158, v154
	v_permlane16_swap_b32_e32 v159, v155
	s_nop 1
	s_waitcnt lgkmcnt(0)
	v_pk_add_f32 v[154:155], v[154:155], v[158:159]
	v_mov_b32_e32 v158, v154
	v_mov_b32_e32 v159, v155
	s_nop 1
	v_permlane32_swap_b32_e32 v158, v154
	v_permlane32_swap_b32_e32 v159, v155
	s_nop 1
	s_and_saveexec_b64 s[12:13], s[42:43]
	s_cbranch_execz .LBB0_503
	s_add_i32 s17, s16, 0
	s_add_i32 s17, s17, 0x25010
	s_waitcnt lgkmcnt(0)
	v_pk_add_f32 v[154:155], v[154:155], v[158:159]
	v_mov_b32_e32 v150, s17
	ds_write_b64 v150, v[154:155]
.LBB0_503:
	s_or_b64 exec, exec, s[12:13]
	v_pk_fma_f32 v[134:135], v[4:5], v[134:135], v[74:75]
	v_lshlrev_b32_e32 v150, 16, v151
	v_pk_fma_f32 v[134:135], v[6:7], v[138:139], v[134:135]
	v_and_b32_e32 v151, 0xffff0000, v151
	v_pk_fma_f32 v[134:135], v[8:9], v[144:145], v[134:135]
	s_nop 0
	v_pk_fma_f32 v[134:135], v[10:11], v[142:143], v[134:135]
	s_nop 0
	v_pk_fma_f32 v[134:135], v[12:13], v[136:137], v[134:135]
	s_nop 0
	v_pk_fma_f32 v[134:135], v[14:15], v[132:133], v[134:135]
	s_nop 0
	v_pk_fma_f32 v[134:135], v[16:17], v[110:111], v[134:135]
	s_nop 0
	v_pk_fma_f32 v[134:135], v[18:19], v[80:81], v[134:135]
	s_nop 0
	v_pk_fma_f32 v[134:135], v[28:29], v[82:83], v[134:135]
	s_nop 0
	v_pk_fma_f32 v[134:135], v[30:31], v[86:87], v[134:135]
	s_nop 0
	v_pk_fma_f32 v[134:135], v[32:33], v[88:89], v[134:135]
	s_nop 0
	v_pk_fma_f32 v[134:135], v[34:35], v[90:91], v[134:135]
	s_nop 0
	v_pk_fma_f32 v[134:135], v[36:37], v[92:93], v[134:135]
	s_nop 0
	v_pk_fma_f32 v[134:135], v[38:39], v[96:97], v[134:135]
	s_nop 0
	v_pk_fma_f32 v[134:135], v[40:41], v[98:99], v[134:135]
	s_nop 0
	v_pk_fma_f32 v[134:135], v[42:43], v[100:101], v[134:135]
	s_nop 0
	v_pk_fma_f32 v[134:135], v[44:45], v[102:103], v[134:135]
	s_nop 0
	v_pk_fma_f32 v[134:135], v[46:47], v[106:107], v[134:135]
	s_nop 0
	v_pk_fma_f32 v[134:135], v[48:49], v[108:109], v[134:135]
	s_nop 0
	v_pk_fma_f32 v[134:135], v[50:51], v[112:113], v[134:135]
	s_nop 0
	v_pk_fma_f32 v[134:135], v[52:53], v[114:115], v[134:135]
	s_nop 0
	v_pk_fma_f32 v[134:135], v[54:55], v[118:119], v[134:135]
	s_nop 0
	v_pk_fma_f32 v[134:135], v[56:57], v[120:121], v[134:135]
	s_nop 0
	v_pk_fma_f32 v[134:135], v[58:59], v[122:123], v[134:135]
	s_nop 0
	v_pk_fma_f32 v[134:135], v[60:61], v[124:125], v[134:135]
	s_nop 0
	v_pk_fma_f32 v[134:135], v[62:63], v[126:127], v[134:135]
	s_nop 0
	v_pk_fma_f32 v[134:135], v[64:65], v[128:129], v[134:135]
	s_nop 0
	v_pk_fma_f32 v[134:135], v[66:67], v[130:131], v[134:135]
	s_nop 0
	v_pk_fma_f32 v[134:135], v[68:69], v[140:141], v[134:135]
	s_nop 0
	v_pk_fma_f32 v[134:135], v[70:71], v[148:149], v[134:135]
	s_nop 0
	v_pk_fma_f32 v[134:135], v[72:73], v[150:151], v[134:135]
	s_nop 0
	v_pk_mul_f32 v[154:155], v[134:135], v[134:135]
	s_waitcnt lgkmcnt(0)
	v_mov_b32_e32 v158, v134
	s_waitcnt lgkmcnt(0)
	v_mov_b32_e32 v159, v154
	v_mov_b32_e32 v154, v135
	v_pk_add_f32 v[154:155], v[158:159], v[154:155]
	s_nop 1
	v_add_f32_dpp v154, v154, v154 quad_perm:[1,0,3,2] row_mask:0xf bank_mask:0xf
	v_add_f32_dpp v155, v155, v155 quad_perm:[1,0,3,2] row_mask:0xf bank_mask:0xf
	s_waitcnt lgkmcnt(0)
	s_nop 0
	s_nop 1
	v_add_f32_dpp v154, v154, v154 quad_perm:[2,3,0,1] row_mask:0xf bank_mask:0xf
	v_add_f32_dpp v155, v155, v155 quad_perm:[2,3,0,1] row_mask:0xf bank_mask:0xf
	s_waitcnt lgkmcnt(0)
	s_nop 0
	s_nop 1
	v_add_f32_dpp v154, v154, v154 row_half_mirror row_mask:0xf bank_mask:0xf
	v_add_f32_dpp v155, v155, v155 row_half_mirror row_mask:0xf bank_mask:0xf
	s_waitcnt lgkmcnt(0)
	s_nop 0
	s_nop 1
	v_add_f32_dpp v154, v154, v154 row_mirror row_mask:0xf bank_mask:0xf
	v_add_f32_dpp v155, v155, v155 row_mirror row_mask:0xf bank_mask:0xf
	s_waitcnt lgkmcnt(0)
	s_nop 0
	v_mov_b32_e32 v158, v154
	v_mov_b32_e32 v159, v155
	s_nop 1
	v_permlane16_swap_b32_e32 v158, v154
	v_permlane16_swap_b32_e32 v159, v155
	s_nop 1
	s_waitcnt lgkmcnt(0)
	v_pk_add_f32 v[154:155], v[154:155], v[158:159]
	v_mov_b32_e32 v158, v154
	v_mov_b32_e32 v159, v155
	s_nop 1
	v_permlane32_swap_b32_e32 v158, v154
	v_permlane32_swap_b32_e32 v159, v155
	s_nop 1
	s_and_saveexec_b64 s[12:13], s[42:43]
	s_cbranch_execz .LBB0_505
	s_add_i32 s17, s16, 0
	s_add_i32 s17, s17, 0x25018
	s_waitcnt lgkmcnt(0)
	v_pk_add_f32 v[154:155], v[154:155], v[158:159]
	v_mov_b32_e32 v158, s17
	ds_write_b64 v158, v[154:155]
.LBB0_505:
	s_or_b64 exec, exec, s[12:13]
	v_pk_fma_f32 v[138:139], v[4:5], v[138:139], v[74:75]
	v_lshlrev_b32_e32 v154, 16, v156
	v_pk_fma_f32 v[138:139], v[6:7], v[144:145], v[138:139]
	v_and_b32_e32 v155, 0xffff0000, v156
	v_pk_fma_f32 v[138:139], v[8:9], v[142:143], v[138:139]
	s_nop 0
	v_pk_fma_f32 v[138:139], v[10:11], v[136:137], v[138:139]
	s_nop 0
	v_pk_fma_f32 v[138:139], v[12:13], v[132:133], v[138:139]
	s_nop 0
	v_pk_fma_f32 v[138:139], v[14:15], v[110:111], v[138:139]
	s_nop 0
	v_pk_fma_f32 v[138:139], v[16:17], v[80:81], v[138:139]
	s_nop 0
	v_pk_fma_f32 v[138:139], v[18:19], v[82:83], v[138:139]
	s_nop 0
	v_pk_fma_f32 v[138:139], v[28:29], v[86:87], v[138:139]
	s_nop 0
	v_pk_fma_f32 v[138:139], v[30:31], v[88:89], v[138:139]
	s_nop 0
	v_pk_fma_f32 v[138:139], v[32:33], v[90:91], v[138:139]
	s_nop 0
	v_pk_fma_f32 v[138:139], v[34:35], v[92:93], v[138:139]
	s_nop 0
	v_pk_fma_f32 v[138:139], v[36:37], v[96:97], v[138:139]
	s_nop 0
	v_pk_fma_f32 v[138:139], v[38:39], v[98:99], v[138:139]
	s_nop 0
	v_pk_fma_f32 v[138:139], v[40:41], v[100:101], v[138:139]
	s_nop 0
	v_pk_fma_f32 v[138:139], v[42:43], v[102:103], v[138:139]
	s_nop 0
	v_pk_fma_f32 v[138:139], v[44:45], v[106:107], v[138:139]
	s_nop 0
	v_pk_fma_f32 v[138:139], v[46:47], v[108:109], v[138:139]
	s_nop 0
	v_pk_fma_f32 v[138:139], v[48:49], v[112:113], v[138:139]
	s_nop 0
	v_pk_fma_f32 v[138:139], v[50:51], v[114:115], v[138:139]
	s_nop 0
	v_pk_fma_f32 v[138:139], v[52:53], v[118:119], v[138:139]
	s_nop 0
	v_pk_fma_f32 v[138:139], v[54:55], v[120:121], v[138:139]
	s_nop 0
	v_pk_fma_f32 v[138:139], v[56:57], v[122:123], v[138:139]
	s_nop 0
	v_pk_fma_f32 v[138:139], v[58:59], v[124:125], v[138:139]
	s_nop 0
	v_pk_fma_f32 v[138:139], v[60:61], v[126:127], v[138:139]
	s_nop 0
	v_pk_fma_f32 v[138:139], v[62:63], v[128:129], v[138:139]
	s_nop 0
	v_pk_fma_f32 v[138:139], v[64:65], v[130:131], v[138:139]
	s_nop 0
	v_pk_fma_f32 v[138:139], v[66:67], v[140:141], v[138:139]
	s_nop 0
	v_pk_fma_f32 v[138:139], v[68:69], v[148:149], v[138:139]
	s_nop 0
	v_pk_fma_f32 v[138:139], v[70:71], v[150:151], v[138:139]
	s_nop 0
	v_pk_fma_f32 v[138:139], v[72:73], v[154:155], v[138:139]
	s_waitcnt lgkmcnt(0)
	v_pk_mul_f32 v[158:159], v[138:139], v[138:139]
	v_mov_b32_e32 v160, v138
	v_mov_b32_e32 v161, v158
	v_mov_b32_e32 v158, v139
	v_pk_add_f32 v[158:159], v[160:161], v[158:159]
	s_nop 1
	v_add_f32_dpp v158, v158, v158 quad_perm:[1,0,3,2] row_mask:0xf bank_mask:0xf
	v_add_f32_dpp v159, v159, v159 quad_perm:[1,0,3,2] row_mask:0xf bank_mask:0xf
	s_waitcnt lgkmcnt(0)
	s_nop 0
	s_nop 1
	v_add_f32_dpp v158, v158, v158 quad_perm:[2,3,0,1] row_mask:0xf bank_mask:0xf
	v_add_f32_dpp v159, v159, v159 quad_perm:[2,3,0,1] row_mask:0xf bank_mask:0xf
	s_waitcnt lgkmcnt(0)
	s_nop 0
	s_nop 1
	v_add_f32_dpp v158, v158, v158 row_half_mirror row_mask:0xf bank_mask:0xf
	v_add_f32_dpp v159, v159, v159 row_half_mirror row_mask:0xf bank_mask:0xf
	s_waitcnt lgkmcnt(0)
	s_nop 0
	s_nop 1
	v_add_f32_dpp v158, v158, v158 row_mirror row_mask:0xf bank_mask:0xf
	v_add_f32_dpp v159, v159, v159 row_mirror row_mask:0xf bank_mask:0xf
	s_waitcnt lgkmcnt(0)
	s_nop 0
	v_mov_b32_e32 v160, v158
	v_mov_b32_e32 v161, v159
	s_nop 1
	v_permlane16_swap_b32_e32 v160, v158
	v_permlane16_swap_b32_e32 v161, v159
	s_nop 1
	s_waitcnt lgkmcnt(0)
	v_pk_add_f32 v[158:159], v[158:159], v[160:161]
	v_mov_b32_e32 v160, v158
	v_mov_b32_e32 v161, v159
	s_nop 1
	v_permlane32_swap_b32_e32 v160, v158
	v_permlane32_swap_b32_e32 v161, v159
	s_nop 1
	s_and_saveexec_b64 s[12:13], s[42:43]
	s_cbranch_execz .LBB0_507
	s_add_i32 s17, s16, 0
	s_add_i32 s17, s17, 0x25020
	s_waitcnt lgkmcnt(0)
	v_pk_add_f32 v[158:159], v[158:159], v[160:161]
	v_mov_b32_e32 v156, s17
	ds_write_b64 v156, v[158:159]
.LBB0_507:
	s_or_b64 exec, exec, s[12:13]
	v_pk_fma_f32 v[144:145], v[4:5], v[144:145], v[74:75]
	v_lshlrev_b32_e32 v156, 16, v157
	v_pk_fma_f32 v[144:145], v[6:7], v[142:143], v[144:145]
	v_and_b32_e32 v157, 0xffff0000, v157
	v_pk_fma_f32 v[144:145], v[8:9], v[136:137], v[144:145]
	s_nop 0
	v_pk_fma_f32 v[144:145], v[10:11], v[132:133], v[144:145]
	s_nop 0
	v_pk_fma_f32 v[144:145], v[12:13], v[110:111], v[144:145]
	s_nop 0
	v_pk_fma_f32 v[144:145], v[14:15], v[80:81], v[144:145]
	s_nop 0
	v_pk_fma_f32 v[144:145], v[16:17], v[82:83], v[144:145]
	s_nop 0
	v_pk_fma_f32 v[144:145], v[18:19], v[86:87], v[144:145]
	s_nop 0
	v_pk_fma_f32 v[144:145], v[28:29], v[88:89], v[144:145]
	s_nop 0
	v_pk_fma_f32 v[144:145], v[30:31], v[90:91], v[144:145]
	s_nop 0
	v_pk_fma_f32 v[144:145], v[32:33], v[92:93], v[144:145]
	s_nop 0
	v_pk_fma_f32 v[144:145], v[34:35], v[96:97], v[144:145]
	s_nop 0
	v_pk_fma_f32 v[144:145], v[36:37], v[98:99], v[144:145]
	s_nop 0
	v_pk_fma_f32 v[144:145], v[38:39], v[100:101], v[144:145]
	s_nop 0
	v_pk_fma_f32 v[144:145], v[40:41], v[102:103], v[144:145]
	s_nop 0
	v_pk_fma_f32 v[144:145], v[42:43], v[106:107], v[144:145]
	s_nop 0
	v_pk_fma_f32 v[144:145], v[44:45], v[108:109], v[144:145]
	s_nop 0
	v_pk_fma_f32 v[144:145], v[46:47], v[112:113], v[144:145]
	s_nop 0
	v_pk_fma_f32 v[144:145], v[48:49], v[114:115], v[144:145]
	s_nop 0
	v_pk_fma_f32 v[144:145], v[50:51], v[118:119], v[144:145]
	s_nop 0
	v_pk_fma_f32 v[144:145], v[52:53], v[120:121], v[144:145]
	s_nop 0
	v_pk_fma_f32 v[144:145], v[54:55], v[122:123], v[144:145]
	s_nop 0
	v_pk_fma_f32 v[144:145], v[56:57], v[124:125], v[144:145]
	s_nop 0
	v_pk_fma_f32 v[144:145], v[58:59], v[126:127], v[144:145]
	s_nop 0
	v_pk_fma_f32 v[144:145], v[60:61], v[128:129], v[144:145]
	s_nop 0
	v_pk_fma_f32 v[144:145], v[62:63], v[130:131], v[144:145]
	s_nop 0
	v_pk_fma_f32 v[144:145], v[64:65], v[140:141], v[144:145]
	s_nop 0
	v_pk_fma_f32 v[144:145], v[66:67], v[148:149], v[144:145]
	s_nop 0
	v_pk_fma_f32 v[144:145], v[68:69], v[150:151], v[144:145]
	s_nop 0
	v_pk_fma_f32 v[144:145], v[70:71], v[154:155], v[144:145]
	s_nop 0
	v_pk_fma_f32 v[144:145], v[72:73], v[156:157], v[144:145]
	s_nop 0
	v_pk_mul_f32 v[158:159], v[144:145], v[144:145]
	s_waitcnt lgkmcnt(0)
	v_mov_b32_e32 v160, v144
	s_waitcnt lgkmcnt(0)
	v_mov_b32_e32 v161, v158
	v_mov_b32_e32 v158, v145
	v_pk_add_f32 v[158:159], v[160:161], v[158:159]
	s_nop 1
	v_add_f32_dpp v158, v158, v158 quad_perm:[1,0,3,2] row_mask:0xf bank_mask:0xf
	v_add_f32_dpp v159, v159, v159 quad_perm:[1,0,3,2] row_mask:0xf bank_mask:0xf
	s_waitcnt lgkmcnt(0)
	s_nop 0
	s_nop 1
	v_add_f32_dpp v158, v158, v158 quad_perm:[2,3,0,1] row_mask:0xf bank_mask:0xf
	v_add_f32_dpp v159, v159, v159 quad_perm:[2,3,0,1] row_mask:0xf bank_mask:0xf
	s_waitcnt lgkmcnt(0)
	s_nop 0
	s_nop 1
	v_add_f32_dpp v158, v158, v158 row_half_mirror row_mask:0xf bank_mask:0xf
	v_add_f32_dpp v159, v159, v159 row_half_mirror row_mask:0xf bank_mask:0xf
	s_waitcnt lgkmcnt(0)
	s_nop 0
	s_nop 1
	v_add_f32_dpp v158, v158, v158 row_mirror row_mask:0xf bank_mask:0xf
	v_add_f32_dpp v159, v159, v159 row_mirror row_mask:0xf bank_mask:0xf
	s_waitcnt lgkmcnt(0)
	s_nop 0
	v_mov_b32_e32 v160, v158
	v_mov_b32_e32 v161, v159
	s_nop 1
	v_permlane16_swap_b32_e32 v160, v158
	v_permlane16_swap_b32_e32 v161, v159
	s_nop 1
	s_waitcnt lgkmcnt(0)
	v_pk_add_f32 v[158:159], v[158:159], v[160:161]
	v_mov_b32_e32 v160, v158
	v_mov_b32_e32 v161, v159
	s_nop 1
	v_permlane32_swap_b32_e32 v160, v158
	v_permlane32_swap_b32_e32 v161, v159
	s_nop 1
	s_and_saveexec_b64 s[12:13], s[42:43]
	s_cbranch_execz .LBB0_509
	s_add_i32 s17, s16, 0
	s_add_i32 s17, s17, 0x25028
	s_waitcnt lgkmcnt(0)
	v_pk_add_f32 v[158:159], v[158:159], v[160:161]
	v_mov_b32_e32 v160, s17
	ds_write_b64 v160, v[158:159]
.LBB0_509:
	s_or_b64 exec, exec, s[12:13]
	v_pk_fma_f32 v[142:143], v[4:5], v[142:143], v[74:75]
	v_lshlrev_b32_e32 v158, 16, v152
	v_pk_fma_f32 v[142:143], v[6:7], v[136:137], v[142:143]
	v_and_b32_e32 v159, 0xffff0000, v152
	v_pk_fma_f32 v[142:143], v[8:9], v[132:133], v[142:143]
	s_nop 0
	v_pk_fma_f32 v[142:143], v[10:11], v[110:111], v[142:143]
	s_nop 0
	v_pk_fma_f32 v[142:143], v[12:13], v[80:81], v[142:143]
	s_nop 0
	v_pk_fma_f32 v[142:143], v[14:15], v[82:83], v[142:143]
	s_nop 0
	v_pk_fma_f32 v[142:143], v[16:17], v[86:87], v[142:143]
	s_nop 0
	v_pk_fma_f32 v[142:143], v[18:19], v[88:89], v[142:143]
	s_nop 0
	v_pk_fma_f32 v[142:143], v[28:29], v[90:91], v[142:143]
	s_nop 0
	v_pk_fma_f32 v[142:143], v[30:31], v[92:93], v[142:143]
	s_nop 0
	v_pk_fma_f32 v[142:143], v[32:33], v[96:97], v[142:143]
	s_nop 0
	v_pk_fma_f32 v[142:143], v[34:35], v[98:99], v[142:143]
	s_nop 0
	v_pk_fma_f32 v[142:143], v[36:37], v[100:101], v[142:143]
	s_nop 0
	v_pk_fma_f32 v[142:143], v[38:39], v[102:103], v[142:143]
	s_nop 0
	v_pk_fma_f32 v[142:143], v[40:41], v[106:107], v[142:143]
	s_nop 0
	v_pk_fma_f32 v[142:143], v[42:43], v[108:109], v[142:143]
	s_nop 0
	v_pk_fma_f32 v[142:143], v[44:45], v[112:113], v[142:143]
	s_nop 0
	v_pk_fma_f32 v[142:143], v[46:47], v[114:115], v[142:143]
	s_nop 0
	v_pk_fma_f32 v[142:143], v[48:49], v[118:119], v[142:143]
	s_nop 0
	v_pk_fma_f32 v[142:143], v[50:51], v[120:121], v[142:143]
	s_nop 0
	v_pk_fma_f32 v[142:143], v[52:53], v[122:123], v[142:143]
	s_nop 0
	v_pk_fma_f32 v[142:143], v[54:55], v[124:125], v[142:143]
	s_nop 0
	v_pk_fma_f32 v[142:143], v[56:57], v[126:127], v[142:143]
	s_nop 0
	v_pk_fma_f32 v[142:143], v[58:59], v[128:129], v[142:143]
	s_nop 0
	v_pk_fma_f32 v[142:143], v[60:61], v[130:131], v[142:143]
	s_nop 0
	v_pk_fma_f32 v[142:143], v[62:63], v[140:141], v[142:143]
	s_nop 0
	v_pk_fma_f32 v[142:143], v[64:65], v[148:149], v[142:143]
	s_nop 0
	v_pk_fma_f32 v[142:143], v[66:67], v[150:151], v[142:143]
	s_nop 0
	v_pk_fma_f32 v[142:143], v[68:69], v[154:155], v[142:143]
	s_nop 0
	v_pk_fma_f32 v[142:143], v[70:71], v[156:157], v[142:143]
	s_nop 0
	v_pk_fma_f32 v[142:143], v[72:73], v[158:159], v[142:143]
	s_waitcnt lgkmcnt(0)
	v_pk_mul_f32 v[160:161], v[142:143], v[142:143]
	v_mov_b32_e32 v162, v142
	v_mov_b32_e32 v163, v160
	v_mov_b32_e32 v160, v143
	v_pk_add_f32 v[160:161], v[162:163], v[160:161]
	s_nop 1
	v_add_f32_dpp v160, v160, v160 quad_perm:[1,0,3,2] row_mask:0xf bank_mask:0xf
	v_add_f32_dpp v161, v161, v161 quad_perm:[1,0,3,2] row_mask:0xf bank_mask:0xf
	s_waitcnt lgkmcnt(0)
	s_nop 0
	s_nop 1
	v_add_f32_dpp v160, v160, v160 quad_perm:[2,3,0,1] row_mask:0xf bank_mask:0xf
	v_add_f32_dpp v161, v161, v161 quad_perm:[2,3,0,1] row_mask:0xf bank_mask:0xf
	s_waitcnt lgkmcnt(0)
	s_nop 0
	s_nop 1
	v_add_f32_dpp v160, v160, v160 row_half_mirror row_mask:0xf bank_mask:0xf
	v_add_f32_dpp v161, v161, v161 row_half_mirror row_mask:0xf bank_mask:0xf
	s_waitcnt lgkmcnt(0)
	s_nop 0
	s_nop 1
	v_add_f32_dpp v160, v160, v160 row_mirror row_mask:0xf bank_mask:0xf
	v_add_f32_dpp v161, v161, v161 row_mirror row_mask:0xf bank_mask:0xf
	s_waitcnt lgkmcnt(0)
	s_nop 0
	v_mov_b32_e32 v162, v160
	v_mov_b32_e32 v163, v161
	s_nop 1
	v_permlane16_swap_b32_e32 v162, v160
	v_permlane16_swap_b32_e32 v163, v161
	s_nop 1
	s_waitcnt lgkmcnt(0)
	v_pk_add_f32 v[160:161], v[160:161], v[162:163]
	v_mov_b32_e32 v162, v160
	v_mov_b32_e32 v163, v161
	s_nop 1
	v_permlane32_swap_b32_e32 v162, v160
	v_permlane32_swap_b32_e32 v163, v161
	s_nop 1
	s_and_saveexec_b64 s[12:13], s[42:43]
	s_cbranch_execz .LBB0_511
	s_add_i32 s17, s16, 0
	s_add_i32 s17, s17, 0x25030
	s_waitcnt lgkmcnt(0)
	v_pk_add_f32 v[160:161], v[160:161], v[162:163]
	v_mov_b32_e32 v152, s17
	ds_write_b64 v152, v[160:161]
.LBB0_511:
	s_or_b64 exec, exec, s[12:13]
	v_pk_fma_f32 v[136:137], v[4:5], v[136:137], v[74:75]
	v_lshlrev_b32_e32 v152, 16, v153
	v_pk_fma_f32 v[136:137], v[6:7], v[132:133], v[136:137]
	v_and_b32_e32 v153, 0xffff0000, v153
	v_pk_fma_f32 v[136:137], v[8:9], v[110:111], v[136:137]
	s_nop 0
	v_pk_fma_f32 v[136:137], v[10:11], v[80:81], v[136:137]
	s_nop 0
	v_pk_fma_f32 v[136:137], v[12:13], v[82:83], v[136:137]
	s_nop 0
	v_pk_fma_f32 v[136:137], v[14:15], v[86:87], v[136:137]
	s_nop 0
	v_pk_fma_f32 v[136:137], v[16:17], v[88:89], v[136:137]
	s_nop 0
	v_pk_fma_f32 v[136:137], v[18:19], v[90:91], v[136:137]
	s_nop 0
	v_pk_fma_f32 v[136:137], v[28:29], v[92:93], v[136:137]
	s_nop 0
	v_pk_fma_f32 v[136:137], v[30:31], v[96:97], v[136:137]
	s_nop 0
	v_pk_fma_f32 v[136:137], v[32:33], v[98:99], v[136:137]
	s_nop 0
	v_pk_fma_f32 v[136:137], v[34:35], v[100:101], v[136:137]
	s_nop 0
	v_pk_fma_f32 v[136:137], v[36:37], v[102:103], v[136:137]
	s_nop 0
	v_pk_fma_f32 v[136:137], v[38:39], v[106:107], v[136:137]
	s_nop 0
	v_pk_fma_f32 v[136:137], v[40:41], v[108:109], v[136:137]
	s_nop 0
	v_pk_fma_f32 v[136:137], v[42:43], v[112:113], v[136:137]
	s_nop 0
	v_pk_fma_f32 v[136:137], v[44:45], v[114:115], v[136:137]
	s_nop 0
	v_pk_fma_f32 v[136:137], v[46:47], v[118:119], v[136:137]
	s_nop 0
	v_pk_fma_f32 v[136:137], v[48:49], v[120:121], v[136:137]
	s_nop 0
	v_pk_fma_f32 v[136:137], v[50:51], v[122:123], v[136:137]
	s_nop 0
	v_pk_fma_f32 v[136:137], v[52:53], v[124:125], v[136:137]
	s_nop 0
	v_pk_fma_f32 v[136:137], v[54:55], v[126:127], v[136:137]
	s_nop 0
	v_pk_fma_f32 v[136:137], v[56:57], v[128:129], v[136:137]
	s_nop 0
	v_pk_fma_f32 v[136:137], v[58:59], v[130:131], v[136:137]
	s_nop 0
	v_pk_fma_f32 v[136:137], v[60:61], v[140:141], v[136:137]
	s_nop 0
	v_pk_fma_f32 v[136:137], v[62:63], v[148:149], v[136:137]
	s_nop 0
	v_pk_fma_f32 v[136:137], v[64:65], v[150:151], v[136:137]
	s_nop 0
	v_pk_fma_f32 v[136:137], v[66:67], v[154:155], v[136:137]
	s_nop 0
	v_pk_fma_f32 v[136:137], v[68:69], v[156:157], v[136:137]
	s_nop 0
	v_pk_fma_f32 v[136:137], v[70:71], v[158:159], v[136:137]
	s_nop 0
	v_pk_fma_f32 v[136:137], v[72:73], v[152:153], v[136:137]
	s_nop 0
	v_pk_mul_f32 v[160:161], v[136:137], v[136:137]
	s_waitcnt lgkmcnt(0)
	v_mov_b32_e32 v162, v136
	s_waitcnt lgkmcnt(0)
	v_mov_b32_e32 v163, v160
	v_mov_b32_e32 v160, v137
	v_pk_add_f32 v[160:161], v[162:163], v[160:161]
	s_nop 1
	v_add_f32_dpp v160, v160, v160 quad_perm:[1,0,3,2] row_mask:0xf bank_mask:0xf
	v_add_f32_dpp v161, v161, v161 quad_perm:[1,0,3,2] row_mask:0xf bank_mask:0xf
	s_waitcnt lgkmcnt(0)
	s_nop 0
	s_nop 1
	v_add_f32_dpp v160, v160, v160 quad_perm:[2,3,0,1] row_mask:0xf bank_mask:0xf
	v_add_f32_dpp v161, v161, v161 quad_perm:[2,3,0,1] row_mask:0xf bank_mask:0xf
	s_waitcnt lgkmcnt(0)
	s_nop 0
	s_nop 1
	v_add_f32_dpp v160, v160, v160 row_half_mirror row_mask:0xf bank_mask:0xf
	v_add_f32_dpp v161, v161, v161 row_half_mirror row_mask:0xf bank_mask:0xf
	s_waitcnt lgkmcnt(0)
	s_nop 0
	s_nop 1
	v_add_f32_dpp v160, v160, v160 row_mirror row_mask:0xf bank_mask:0xf
	v_add_f32_dpp v161, v161, v161 row_mirror row_mask:0xf bank_mask:0xf
	s_waitcnt lgkmcnt(0)
	s_nop 0
	v_mov_b32_e32 v162, v160
	v_mov_b32_e32 v163, v161
	s_nop 1
	v_permlane16_swap_b32_e32 v162, v160
	v_permlane16_swap_b32_e32 v163, v161
	s_nop 1
	s_waitcnt lgkmcnt(0)
	v_pk_add_f32 v[160:161], v[160:161], v[162:163]
	v_mov_b32_e32 v162, v160
	v_mov_b32_e32 v163, v161
	s_nop 1
	v_permlane32_swap_b32_e32 v162, v160
	v_permlane32_swap_b32_e32 v163, v161
	s_nop 1
	s_and_saveexec_b64 s[12:13], s[42:43]
	s_cbranch_execz .LBB0_513
	s_add_i32 s17, s16, 0
	s_add_i32 s17, s17, 0x25038
	s_waitcnt lgkmcnt(0)
	v_pk_add_f32 v[160:161], v[160:161], v[162:163]
	v_mov_b32_e32 v162, s17
	ds_write_b64 v162, v[160:161]
.LBB0_513:
	s_or_b64 exec, exec, s[12:13]
	v_pk_fma_f32 v[132:133], v[4:5], v[132:133], v[74:75]
	v_lshlrev_b32_e32 v160, 16, v146
	v_pk_fma_f32 v[132:133], v[6:7], v[110:111], v[132:133]
	v_and_b32_e32 v161, 0xffff0000, v146
	v_pk_fma_f32 v[132:133], v[8:9], v[80:81], v[132:133]
	s_nop 0
	v_pk_fma_f32 v[132:133], v[10:11], v[82:83], v[132:133]
	s_nop 0
	v_pk_fma_f32 v[132:133], v[12:13], v[86:87], v[132:133]
	s_nop 0
	v_pk_fma_f32 v[132:133], v[14:15], v[88:89], v[132:133]
	s_nop 0
	v_pk_fma_f32 v[132:133], v[16:17], v[90:91], v[132:133]
	s_nop 0
	v_pk_fma_f32 v[132:133], v[18:19], v[92:93], v[132:133]
	s_nop 0
	v_pk_fma_f32 v[132:133], v[28:29], v[96:97], v[132:133]
	s_nop 0
	v_pk_fma_f32 v[132:133], v[30:31], v[98:99], v[132:133]
	s_nop 0
	v_pk_fma_f32 v[132:133], v[32:33], v[100:101], v[132:133]
	s_nop 0
	v_pk_fma_f32 v[132:133], v[34:35], v[102:103], v[132:133]
	s_nop 0
	v_pk_fma_f32 v[132:133], v[36:37], v[106:107], v[132:133]
	s_nop 0
	v_pk_fma_f32 v[132:133], v[38:39], v[108:109], v[132:133]
	s_nop 0
	v_pk_fma_f32 v[132:133], v[40:41], v[112:113], v[132:133]
	s_nop 0
	v_pk_fma_f32 v[132:133], v[42:43], v[114:115], v[132:133]
	s_nop 0
	v_pk_fma_f32 v[132:133], v[44:45], v[118:119], v[132:133]
	s_nop 0
	v_pk_fma_f32 v[132:133], v[46:47], v[120:121], v[132:133]
	s_nop 0
	v_pk_fma_f32 v[132:133], v[48:49], v[122:123], v[132:133]
	s_nop 0
	v_pk_fma_f32 v[132:133], v[50:51], v[124:125], v[132:133]
	s_nop 0
	v_pk_fma_f32 v[132:133], v[52:53], v[126:127], v[132:133]
	s_nop 0
	v_pk_fma_f32 v[132:133], v[54:55], v[128:129], v[132:133]
	s_nop 0
	v_pk_fma_f32 v[132:133], v[56:57], v[130:131], v[132:133]
	s_nop 0
	v_pk_fma_f32 v[132:133], v[58:59], v[140:141], v[132:133]
	s_nop 0
	v_pk_fma_f32 v[132:133], v[60:61], v[148:149], v[132:133]
	s_nop 0
	v_pk_fma_f32 v[132:133], v[62:63], v[150:151], v[132:133]
	s_nop 0
	v_pk_fma_f32 v[132:133], v[64:65], v[154:155], v[132:133]
	s_nop 0
	v_pk_fma_f32 v[132:133], v[66:67], v[156:157], v[132:133]
	s_nop 0
	v_pk_fma_f32 v[132:133], v[68:69], v[158:159], v[132:133]
	s_nop 0
	v_pk_fma_f32 v[132:133], v[70:71], v[152:153], v[132:133]
	s_nop 0
	v_pk_fma_f32 v[132:133], v[72:73], v[160:161], v[132:133]
	s_waitcnt lgkmcnt(0)
	v_pk_mul_f32 v[162:163], v[132:133], v[132:133]
	v_mov_b32_e32 v164, v132
	v_mov_b32_e32 v165, v162
	v_mov_b32_e32 v162, v133
	v_pk_add_f32 v[162:163], v[164:165], v[162:163]
	s_nop 1
	v_add_f32_dpp v162, v162, v162 quad_perm:[1,0,3,2] row_mask:0xf bank_mask:0xf
	v_add_f32_dpp v163, v163, v163 quad_perm:[1,0,3,2] row_mask:0xf bank_mask:0xf
	s_waitcnt lgkmcnt(0)
	s_nop 0
	s_nop 1
	v_add_f32_dpp v162, v162, v162 quad_perm:[2,3,0,1] row_mask:0xf bank_mask:0xf
	v_add_f32_dpp v163, v163, v163 quad_perm:[2,3,0,1] row_mask:0xf bank_mask:0xf
	s_waitcnt lgkmcnt(0)
	s_nop 0
	s_nop 1
	v_add_f32_dpp v162, v162, v162 row_half_mirror row_mask:0xf bank_mask:0xf
	v_add_f32_dpp v163, v163, v163 row_half_mirror row_mask:0xf bank_mask:0xf
	s_waitcnt lgkmcnt(0)
	s_nop 0
	s_nop 1
	v_add_f32_dpp v162, v162, v162 row_mirror row_mask:0xf bank_mask:0xf
	v_add_f32_dpp v163, v163, v163 row_mirror row_mask:0xf bank_mask:0xf
	s_waitcnt lgkmcnt(0)
	s_nop 0
	v_mov_b32_e32 v164, v162
	v_mov_b32_e32 v165, v163
	s_nop 1
	v_permlane16_swap_b32_e32 v164, v162
	v_permlane16_swap_b32_e32 v165, v163
	s_nop 1
	s_waitcnt lgkmcnt(0)
	v_pk_add_f32 v[162:163], v[162:163], v[164:165]
	v_mov_b32_e32 v164, v162
	v_mov_b32_e32 v165, v163
	s_nop 1
	v_permlane32_swap_b32_e32 v164, v162
	v_permlane32_swap_b32_e32 v165, v163
	s_nop 1
	s_and_saveexec_b64 s[12:13], s[42:43]
	s_cbranch_execz .LBB0_515
	s_add_i32 s17, s16, 0
	s_add_i32 s17, s17, 0x25040
	s_waitcnt lgkmcnt(0)
	v_pk_add_f32 v[162:163], v[162:163], v[164:165]
	v_mov_b32_e32 v146, s17
	ds_write_b64 v146, v[162:163]
.LBB0_515:
	s_or_b64 exec, exec, s[12:13]
	v_pk_fma_f32 v[110:111], v[4:5], v[110:111], v[74:75]
	v_lshlrev_b32_e32 v146, 16, v147
	v_pk_fma_f32 v[110:111], v[6:7], v[80:81], v[110:111]
	v_and_b32_e32 v147, 0xffff0000, v147
	v_pk_fma_f32 v[110:111], v[8:9], v[82:83], v[110:111]
	s_nop 0
	v_pk_fma_f32 v[110:111], v[10:11], v[86:87], v[110:111]
	s_nop 0
	v_pk_fma_f32 v[110:111], v[12:13], v[88:89], v[110:111]
	s_nop 0
	v_pk_fma_f32 v[110:111], v[14:15], v[90:91], v[110:111]
	s_nop 0
	v_pk_fma_f32 v[110:111], v[16:17], v[92:93], v[110:111]
	s_nop 0
	v_pk_fma_f32 v[110:111], v[18:19], v[96:97], v[110:111]
	s_nop 0
	v_pk_fma_f32 v[110:111], v[28:29], v[98:99], v[110:111]
	s_nop 0
	v_pk_fma_f32 v[110:111], v[30:31], v[100:101], v[110:111]
	s_nop 0
	v_pk_fma_f32 v[110:111], v[32:33], v[102:103], v[110:111]
	s_nop 0
	v_pk_fma_f32 v[110:111], v[34:35], v[106:107], v[110:111]
	s_nop 0
	v_pk_fma_f32 v[110:111], v[36:37], v[108:109], v[110:111]
	s_nop 0
	v_pk_fma_f32 v[110:111], v[38:39], v[112:113], v[110:111]
	s_nop 0
	v_pk_fma_f32 v[110:111], v[40:41], v[114:115], v[110:111]
	s_nop 0
	v_pk_fma_f32 v[110:111], v[42:43], v[118:119], v[110:111]
	s_nop 0
	v_pk_fma_f32 v[110:111], v[44:45], v[120:121], v[110:111]
	s_nop 0
	v_pk_fma_f32 v[110:111], v[46:47], v[122:123], v[110:111]
	s_nop 0
	v_pk_fma_f32 v[110:111], v[48:49], v[124:125], v[110:111]
	s_nop 0
	v_pk_fma_f32 v[110:111], v[50:51], v[126:127], v[110:111]
	s_nop 0
	v_pk_fma_f32 v[110:111], v[52:53], v[128:129], v[110:111]
	s_nop 0
	v_pk_fma_f32 v[110:111], v[54:55], v[130:131], v[110:111]
	s_nop 0
	v_pk_fma_f32 v[110:111], v[56:57], v[140:141], v[110:111]
	s_nop 0
	v_pk_fma_f32 v[110:111], v[58:59], v[148:149], v[110:111]
	s_nop 0
	v_pk_fma_f32 v[110:111], v[60:61], v[150:151], v[110:111]
	s_nop 0
	v_pk_fma_f32 v[110:111], v[62:63], v[154:155], v[110:111]
	s_nop 0
	v_pk_fma_f32 v[110:111], v[64:65], v[156:157], v[110:111]
	s_nop 0
	v_pk_fma_f32 v[110:111], v[66:67], v[158:159], v[110:111]
	s_nop 0
	v_pk_fma_f32 v[110:111], v[68:69], v[152:153], v[110:111]
	s_nop 0
	v_pk_fma_f32 v[110:111], v[70:71], v[160:161], v[110:111]
	s_nop 0
	v_pk_fma_f32 v[110:111], v[72:73], v[146:147], v[110:111]
	s_nop 0
	v_pk_mul_f32 v[162:163], v[110:111], v[110:111]
	s_waitcnt lgkmcnt(0)
	v_mov_b32_e32 v164, v110
	s_waitcnt lgkmcnt(0)
	v_mov_b32_e32 v165, v162
	v_mov_b32_e32 v162, v111
	v_pk_add_f32 v[162:163], v[164:165], v[162:163]
	s_nop 1
	v_add_f32_dpp v162, v162, v162 quad_perm:[1,0,3,2] row_mask:0xf bank_mask:0xf
	v_add_f32_dpp v163, v163, v163 quad_perm:[1,0,3,2] row_mask:0xf bank_mask:0xf
	s_waitcnt lgkmcnt(0)
	s_nop 0
	s_nop 1
	v_add_f32_dpp v162, v162, v162 quad_perm:[2,3,0,1] row_mask:0xf bank_mask:0xf
	v_add_f32_dpp v163, v163, v163 quad_perm:[2,3,0,1] row_mask:0xf bank_mask:0xf
	s_waitcnt lgkmcnt(0)
	s_nop 0
	s_nop 1
	v_add_f32_dpp v162, v162, v162 row_half_mirror row_mask:0xf bank_mask:0xf
	v_add_f32_dpp v163, v163, v163 row_half_mirror row_mask:0xf bank_mask:0xf
	s_waitcnt lgkmcnt(0)
	s_nop 0
	s_nop 1
	v_add_f32_dpp v162, v162, v162 row_mirror row_mask:0xf bank_mask:0xf
	v_add_f32_dpp v163, v163, v163 row_mirror row_mask:0xf bank_mask:0xf
	s_waitcnt lgkmcnt(0)
	s_nop 0
	v_mov_b32_e32 v164, v162
	v_mov_b32_e32 v165, v163
	s_nop 1
	v_permlane16_swap_b32_e32 v164, v162
	v_permlane16_swap_b32_e32 v165, v163
	s_nop 1
	s_waitcnt lgkmcnt(0)
	v_pk_add_f32 v[162:163], v[162:163], v[164:165]
	v_mov_b32_e32 v164, v162
	v_mov_b32_e32 v165, v163
	s_nop 1
	v_permlane32_swap_b32_e32 v164, v162
	v_permlane32_swap_b32_e32 v165, v163
	s_nop 1
	s_and_saveexec_b64 s[12:13], s[42:43]
	s_cbranch_execz .LBB0_517
	s_add_i32 s17, s16, 0
	s_add_i32 s17, s17, 0x25048
	s_waitcnt lgkmcnt(0)
	v_pk_add_f32 v[162:163], v[162:163], v[164:165]
	v_mov_b32_e32 v164, s17
	ds_write_b64 v164, v[162:163]
.LBB0_517:
	s_or_b64 exec, exec, s[12:13]
	v_pk_fma_f32 v[80:81], v[4:5], v[80:81], v[74:75]
	s_nop 0
	v_pk_fma_f32 v[80:81], v[6:7], v[82:83], v[80:81]
	v_lshlrev_b32_e32 v82, 16, v178
	v_pk_fma_f32 v[80:81], v[8:9], v[86:87], v[80:81]
	v_and_b32_e32 v83, 0xffff0000, v178
	v_pk_fma_f32 v[80:81], v[10:11], v[88:89], v[80:81]
	s_nop 0
	v_pk_fma_f32 v[80:81], v[12:13], v[90:91], v[80:81]
	s_nop 0
	v_pk_fma_f32 v[80:81], v[14:15], v[92:93], v[80:81]
	s_nop 0
	v_pk_fma_f32 v[80:81], v[16:17], v[96:97], v[80:81]
	s_nop 0
	v_pk_fma_f32 v[80:81], v[18:19], v[98:99], v[80:81]
	s_nop 0
	v_pk_fma_f32 v[80:81], v[28:29], v[100:101], v[80:81]
	s_nop 0
	v_pk_fma_f32 v[80:81], v[30:31], v[102:103], v[80:81]
	s_nop 0
	v_pk_fma_f32 v[80:81], v[32:33], v[106:107], v[80:81]
	s_nop 0
	v_pk_fma_f32 v[80:81], v[34:35], v[108:109], v[80:81]
	s_nop 0
	v_pk_fma_f32 v[80:81], v[36:37], v[112:113], v[80:81]
	s_nop 0
	v_pk_fma_f32 v[80:81], v[38:39], v[114:115], v[80:81]
	s_nop 0
	v_pk_fma_f32 v[80:81], v[40:41], v[118:119], v[80:81]
	s_nop 0
	v_pk_fma_f32 v[80:81], v[42:43], v[120:121], v[80:81]
	s_nop 0
	v_pk_fma_f32 v[80:81], v[44:45], v[122:123], v[80:81]
	s_nop 0
	v_pk_fma_f32 v[80:81], v[46:47], v[124:125], v[80:81]
	s_nop 0
	v_pk_fma_f32 v[80:81], v[48:49], v[126:127], v[80:81]
	s_nop 0
	v_pk_fma_f32 v[80:81], v[50:51], v[128:129], v[80:81]
	s_nop 0
	v_pk_fma_f32 v[80:81], v[52:53], v[130:131], v[80:81]
	s_nop 0
	v_pk_fma_f32 v[80:81], v[54:55], v[140:141], v[80:81]
	s_nop 0
	v_pk_fma_f32 v[80:81], v[56:57], v[148:149], v[80:81]
	s_nop 0
	v_pk_fma_f32 v[80:81], v[58:59], v[150:151], v[80:81]
	s_nop 0
	v_pk_fma_f32 v[80:81], v[60:61], v[154:155], v[80:81]
	s_nop 0
	v_pk_fma_f32 v[80:81], v[62:63], v[156:157], v[80:81]
	s_nop 0
	v_pk_fma_f32 v[80:81], v[64:65], v[158:159], v[80:81]
	s_nop 0
	v_pk_fma_f32 v[80:81], v[66:67], v[152:153], v[80:81]
	s_nop 0
	v_pk_fma_f32 v[80:81], v[68:69], v[160:161], v[80:81]
	s_nop 0
	v_pk_fma_f32 v[80:81], v[70:71], v[146:147], v[80:81]
	s_nop 0
	v_pk_fma_f32 v[80:81], v[72:73], v[82:83], v[80:81]
	s_nop 0
	v_pk_mul_f32 v[82:83], v[80:81], v[80:81]
	v_mov_b32_e32 v86, v80
	v_mov_b32_e32 v87, v82
	v_mov_b32_e32 v82, v81
	v_pk_add_f32 v[82:83], v[86:87], v[82:83]
	s_nop 1
	v_add_f32_dpp v82, v82, v82 quad_perm:[1,0,3,2] row_mask:0xf bank_mask:0xf
	v_add_f32_dpp v83, v83, v83 quad_perm:[1,0,3,2] row_mask:0xf bank_mask:0xf
	s_waitcnt lgkmcnt(0)
	s_nop 0
	s_nop 1
	v_add_f32_dpp v82, v82, v82 quad_perm:[2,3,0,1] row_mask:0xf bank_mask:0xf
	v_add_f32_dpp v83, v83, v83 quad_perm:[2,3,0,1] row_mask:0xf bank_mask:0xf
	s_waitcnt lgkmcnt(0)
	s_nop 0
	s_nop 1
	v_add_f32_dpp v82, v82, v82 row_half_mirror row_mask:0xf bank_mask:0xf
	v_add_f32_dpp v83, v83, v83 row_half_mirror row_mask:0xf bank_mask:0xf
	s_waitcnt lgkmcnt(0)
	s_nop 0
	s_nop 1
	v_add_f32_dpp v82, v82, v82 row_mirror row_mask:0xf bank_mask:0xf
	v_add_f32_dpp v83, v83, v83 row_mirror row_mask:0xf bank_mask:0xf
	s_waitcnt lgkmcnt(0)
	s_nop 0
	v_mov_b32_e32 v86, v82
	v_mov_b32_e32 v87, v83
	s_nop 1
	v_permlane16_swap_b32_e32 v86, v82
	v_permlane16_swap_b32_e32 v87, v83
	s_nop 1
	s_waitcnt lgkmcnt(0)
	v_pk_add_f32 v[82:83], v[82:83], v[86:87]
	v_mov_b32_e32 v86, v82
	v_mov_b32_e32 v87, v83
	s_nop 1
	v_permlane32_swap_b32_e32 v86, v82
	v_permlane32_swap_b32_e32 v87, v83
	s_nop 1
	s_and_saveexec_b64 s[12:13], s[42:43]
	s_cbranch_execz .LBB0_519
	s_add_i32 s17, s16, 0
	s_add_i32 s17, s17, 0x25050
	s_waitcnt lgkmcnt(0)
	v_pk_add_f32 v[82:83], v[82:83], v[86:87]
	v_mov_b32_e32 v86, s17
	ds_write_b64 v86, v[82:83]
.LBB0_519:
	s_or_b64 exec, exec, s[12:13]
	s_waitcnt lgkmcnt(0)
	s_barrier
	s_and_saveexec_b64 s[12:13], s[46:47]
	s_cbranch_execz .LBB0_521
	ds_read2_b64 v[86:89], v168 offset1:11
	ds_read2_b64 v[90:93], v168 offset0:22 offset1:33
	ds_read2_b64 v[96:99], v168 offset0:44 offset1:55
	ds_read2_b64 v[100:103], v168 offset0:66 offset1:77
	s_mov_b32 s18, 0x3a800000
	s_waitcnt lgkmcnt(0)
	v_pk_add_f32 v[82:83], v[86:87], 0 op_sel_hi:[1,0]
	s_nop 0
	v_pk_add_f32 v[82:83], v[82:83], v[88:89]
	s_waitcnt lgkmcnt(0)
	v_pk_add_f32 v[82:83], v[82:83], v[90:91]
	s_nop 0
	v_pk_add_f32 v[82:83], v[82:83], v[92:93]
	s_waitcnt lgkmcnt(0)
	v_pk_add_f32 v[82:83], v[82:83], v[96:97]
	s_nop 0
	v_pk_add_f32 v[82:83], v[82:83], v[98:99]
	s_waitcnt lgkmcnt(0)
	v_pk_add_f32 v[82:83], v[82:83], v[100:101]
	s_nop 0
	v_pk_add_f32 v[82:83], v[82:83], v[102:103]
	s_nop 0
	v_pk_mul_f32 v[82:83], v[82:83], s[18:19] op_sel_hi:[1,0]
	s_nop 0
	v_fma_f32 v83, -v82, v82, v83
	v_max_f32_e32 v83, 0, v83
	v_add_f32_e32 v83, 0x358637bd, v83
	v_mul_f32_e32 v86, 0x4f800000, v83
	v_cmp_gt_f32_e32 vcc, s91, v83
	s_nop 1
	v_cndmask_b32_e32 v83, v83, v86, vcc
	v_sqrt_f32_e32 v86, v83
	s_nop 0
	v_add_u32_e32 v87, -1, v86
	v_add_u32_e32 v88, 1, v86
	v_fma_f32 v89, -v87, v86, v83
	v_fma_f32 v90, -v88, v86, v83
	v_cmp_ge_f32_e64 s[48:49], 0, v89
	s_nop 1
	v_cndmask_b32_e64 v86, v86, v87, s[48:49]
	v_cmp_lt_f32_e64 s[48:49], 0, v90
	s_nop 1
	v_cndmask_b32_e64 v86, v86, v88, s[48:49]
	v_mul_f32_e32 v87, 0x37800000, v86
	v_cndmask_b32_e32 v86, v86, v87, vcc
	v_cmp_class_f32_e32 vcc, v83, v202
	s_nop 1
	v_cndmask_b32_e32 v83, v86, v83, vcc
	v_div_scale_f32 v86, s[18:19], v83, v83, 1.0
	v_rcp_f32_e32 v87, v86
	s_nop 0
	v_fma_f32 v88, -v86, v87, 1.0
	v_fmac_f32_e32 v87, v88, v87
	v_div_scale_f32 v88, vcc, 1.0, v83, 1.0
	v_mul_f32_e32 v89, v88, v87
	v_fma_f32 v90, -v86, v89, v88
	v_fmac_f32_e32 v89, v90, v87
	v_fma_f32 v86, -v86, v89, v88
	v_div_fmas_f32 v86, v86, v87, v89
	v_div_fixup_f32 v83, v86, v83, 1.0
	ds_write_b64 v169, v[82:83]

.LBB0_542:
	v_readlane_b32 s13, v253, 18
	s_add_i32 s12, s12, 10
	s_nop 0
	v_mov_b32_e32 v82, s13
	ds_read_b64 v[82:83], v82
	s_ashr_i32 s13, s12, 31
	s_lshl_b64 s[12:13], s[12:13], 11
	s_waitcnt lgkmcnt(0)
	v_pk_add_f32 v[80:81], v[80:81], v[82:83] op_sel_hi:[1,0] neg_lo:[0,1] neg_hi:[0,1]
	s_nop 0
	v_pk_mul_f32 v[80:81], v[82:83], v[80:81] op_sel:[1,0]
	s_nop 0
	v_pk_fma_f32 v[80:81], v[76:77], v[80:81], v[78:79]
	s_nop 0
	v_mul_f32_e32 v82, 0xbfb8aa3b, v81
	v_mul_f32_e32 v83, 0xbfb8aa3b, v80
	v_exp_f32_e32 v82, v82
	v_exp_f32_e32 v83, v83
	v_add_f32_e32 v82, 1.0, v82
	v_add_f32_e32 v86, 1.0, v83
	v_rcp_f32_e32 v83, v82
	v_rcp_f32_e32 v82, v86
	s_nop 0
	v_pk_mul_f32 v[80:81], v[80:81], v[82:83]
	s_nop 0
	v_cvt_pk_bf16_f32 v82, v80, v81
	v_lshl_add_u64 v[80:81], v[26:27], 0, s[12:13]
	global_store_dword v[80:81], v82, off
	s_branch .LBB0_496
	s_nop 0
	s_nop 0
	s_nop 0
	s_nop 0
